# hand-written SWIGLU / GLU / RETT epilogues: write-through (sc1) stores for a workgroup's last unit of the phase
# speedup vs baseline: 1.0013x; 1.0013x over previous
.Lrettk_fast:
	s_and_b64 vcc, exec, s[0:1]
	s_cbranch_vccnz .Lrettk_fast_wt
	v_mov_b32_e32 v148, v162
	v_cvt_f32_i32_e32 v160, v202
	v_add_u32_e32 v161, 16, v202
	v_cvt_f32_i32_e32 v161, v161
	v_add_u32_e32 v162, 32, v202
	v_cvt_f32_i32_e32 v162, v162
	v_add_u32_e32 v163, 48, v202
	v_cvt_f32_i32_e32 v163, v163
	v_mul_f32_e32 v160, 0xbe549a78, v160
	v_mul_f32_e32 v161, 0xbe549a78, v161
	v_mul_f32_e32 v162, 0xbe549a78, v162
	v_mul_f32_e32 v163, 0xbe549a78, v163
	v_exp_f32_e32 v160, v160
	v_exp_f32_e32 v161, v161
	v_exp_f32_e32 v162, v162
	v_exp_f32_e32 v163, v163
	v_mov_b32_e32 v138, 0x3e22f983
	v_mov_b32_e32 v139, 0x3e22f983
	v_mov_b32_e32 v140, 0x3d800000
	v_mov_b32_e32 v141, 0x3d800000
	s_cmp_eq_u32 s68, 0
	s_cselect_b32 s6, 6, 0
	s_cselect_b32 s7, -1, 63
	s_cmp_lt_i32 s65, 64
	s_cselect_b32 s8, 1.0, 0
	v_readlane_b32 s4, v253, 35
	v_mov_b32_e32 v176, s4
	ds_read_b64 v[174:175], v176
	s_lshl_b32 s4, s65, 3
	s_add_i32 s4, s4, s66
	s_lshl_b32 s4, s4, 3
	s_lshl_b32 s5, s68, 1
	s_add_i32 s4, s4, s5
	s_lshl_b32 s4, s4, 3
	s_lshl_b32 s5, s30, 1
	s_add_i32 s4, s4, s5
	s_lshl_b32 s4, s4, 10
	s_mov_b32 s5, 0
	v_and_b32_e32 v176, 1, v203
	v_lshrrev_b32_e32 v177, 1, v203
	v_lshl_add_u32 v177, v177, 5, v202
	v_lshlrev_b32_e32 v177, 3, v177
	v_lshl_add_u32 v176, v176, 9, v177
	v_lshlrev_b32_e32 v176, 1, v176
	v_mov_b32_e32 v177, 0
	s_waitcnt lgkmcnt(0)
	v_lshl_add_u64 v[172:173], v[174:175], 0, s[4:5]
	v_lshl_add_u64 v[172:173], v[172:173], 0, v[176:177]
	s_mov_b64 s[4:5], 0x8000
	v_lshl_add_u64 v[174:175], v[172:173], 0, s[4:5]
	s_mov_b64 s[2:3], 0x2000
	s_mov_b64 s[28:29], 0x3e000
	v_mov_b32_e32 v130, v148
	v_lshrrev_b32_e32 v130, s6, v130
	v_and_b32_e32 v130, s7, v130
	v_cvt_f32_i32_e32 v130, v130
	v_mul_f32_e32 v130, s8, v130
	v_add_u32_e32 v131, 1, v148
	v_lshrrev_b32_e32 v131, s6, v131
	v_and_b32_e32 v131, s7, v131
	v_cvt_f32_i32_e32 v131, v131
	v_mul_f32_e32 v131, s8, v131
	v_add_u32_e32 v132, 2, v148
	v_lshrrev_b32_e32 v132, s6, v132
	v_and_b32_e32 v132, s7, v132
	v_cvt_f32_i32_e32 v132, v132
	v_mul_f32_e32 v132, s8, v132
	v_add_u32_e32 v133, 3, v148
	v_lshrrev_b32_e32 v133, s6, v133
	v_and_b32_e32 v133, s7, v133
	v_cvt_f32_i32_e32 v133, v133
	v_mul_f32_e32 v133, s8, v133
	v_add_u32_e32 v134, 16, v148
	v_lshrrev_b32_e32 v134, s6, v134
	v_and_b32_e32 v134, s7, v134
	v_cvt_f32_i32_e32 v134, v134
	v_mul_f32_e32 v134, s8, v134
	v_add_u32_e32 v135, 17, v148
	v_lshrrev_b32_e32 v135, s6, v135
	v_and_b32_e32 v135, s7, v135
	v_cvt_f32_i32_e32 v135, v135
	v_mul_f32_e32 v135, s8, v135
	v_add_u32_e32 v136, 18, v148
	v_lshrrev_b32_e32 v136, s6, v136
	v_and_b32_e32 v136, s7, v136
	v_cvt_f32_i32_e32 v136, v136
	v_mul_f32_e32 v136, s8, v136
	v_add_u32_e32 v137, 19, v148
	v_lshrrev_b32_e32 v137, s6, v137
	v_and_b32_e32 v137, s7, v137
	v_cvt_f32_i32_e32 v137, v137
	v_mul_f32_e32 v137, s8, v137
	v_mov_b32_e32 v142, v160
	v_pk_mul_f32 v[206:207], v[130:131], v[142:143] op_sel_hi:[1,0]
	v_pk_mul_f32 v[208:209], v[132:133], v[142:143] op_sel_hi:[1,0]
	v_pk_mul_f32 v[210:211], v[134:135], v[142:143] op_sel_hi:[1,0]
	v_pk_mul_f32 v[212:213], v[136:137], v[142:143] op_sel_hi:[1,0]
	v_pk_mul_f32 v[206:207], v[206:207], v[138:139]
	v_sin_f32_e32 v214, v206
	v_pk_mul_f32 v[208:209], v[208:209], v[138:139]
	v_sin_f32_e32 v215, v207
	v_pk_mul_f32 v[210:211], v[210:211], v[138:139]
	v_sin_f32_e32 v216, v208
	v_pk_mul_f32 v[212:213], v[212:213], v[138:139]
	v_sin_f32_e32 v217, v209
	v_pk_mul_f32 v[214:215], v[214:215], v[140:141]
	v_sin_f32_e32 v218, v210
	v_pk_mul_f32 v[216:217], v[216:217], v[140:141]
	v_sin_f32_e32 v219, v211
	v_pk_mul_f32 v[144:145], v[62:63], v[214:215]
	v_sin_f32_e32 v220, v212
	v_pk_mul_f32 v[218:219], v[218:219], v[140:141]
	v_sin_f32_e32 v221, v213
	v_pk_mul_f32 v[146:147], v[64:65], v[216:217]
	v_cos_f32_e32 v206, v206
	v_pk_mul_f32 v[220:221], v[220:221], v[140:141]
	v_cos_f32_e32 v207, v207
	v_mov_b32_e32 v142, v161
	v_cos_f32_e32 v208, v208
	v_pk_mul_f32 v[206:207], v[206:207], v[140:141]
	v_cos_f32_e32 v209, v209
	v_pk_fma_f32 v[222:223], v[126:127], v[206:207], v[144:145] neg_lo:[0,0,1] neg_hi:[0,0,1]
	v_cos_f32_e32 v210, v210
	v_pk_mul_f32 v[208:209], v[208:209], v[140:141]
	v_cos_f32_e32 v211, v211
	v_pk_mul_f32 v[144:145], v[126:127], v[214:215]
	v_cos_f32_e32 v212, v212
	v_pk_mul_f32 v[210:211], v[210:211], v[140:141]
	v_cos_f32_e32 v213, v213
	v_pk_fma_f32 v[164:165], v[62:63], v[206:207], v[144:145]
	v_pk_mul_f32 v[212:213], v[212:213], v[140:141]
	v_pk_fma_f32 v[224:225], v[128:129], v[208:209], v[146:147] neg_lo:[0,0,1] neg_hi:[0,0,1]
	v_pk_mul_f32 v[146:147], v[128:129], v[216:217]
	v_pk_fma_f32 v[166:167], v[64:65], v[208:209], v[146:147]
	v_pk_mul_f32 v[144:145], v[54:55], v[218:219]
	v_pk_fma_f32 v[226:227], v[118:119], v[210:211], v[144:145] neg_lo:[0,0,1] neg_hi:[0,0,1]
	v_pk_mul_f32 v[144:145], v[118:119], v[218:219]
	v_pk_fma_f32 v[168:169], v[54:55], v[210:211], v[144:145]
	v_pk_mul_f32 v[146:147], v[56:57], v[220:221]
	v_pk_fma_f32 v[228:229], v[120:121], v[212:213], v[146:147] neg_lo:[0,0,1] neg_hi:[0,0,1]
	v_pk_mul_f32 v[146:147], v[120:121], v[220:221]
	v_pk_fma_f32 v[170:171], v[56:57], v[212:213], v[146:147]
	v_cvt_pk_bf16_f32 v222, v222, v223
	v_cvt_pk_bf16_f32 v223, v224, v225
	v_cvt_pk_bf16_f32 v224, v226, v227
	v_cvt_pk_bf16_f32 v225, v228, v229
	v_cvt_pk_bf16_f32 v164, v164, v165
	v_cvt_pk_bf16_f32 v165, v166, v167
	v_cvt_pk_bf16_f32 v166, v168, v169
	v_cvt_pk_bf16_f32 v167, v170, v171
	v_permlane16_swap_b32_e32 v222, v224
	v_permlane16_swap_b32_e32 v223, v225
	v_permlane16_swap_b32_e32 v164, v166
	v_permlane16_swap_b32_e32 v165, v167
	global_store_dwordx4 v[172:173], v[222:225], off
	global_store_dwordx4 v[174:175], v[164:167], off
	v_pk_mul_f32 v[236:237], v[130:131], v[142:143] op_sel_hi:[1,0]
	v_pk_mul_f32 v[238:239], v[132:133], v[142:143] op_sel_hi:[1,0]
	v_pk_mul_f32 v[240:241], v[134:135], v[142:143] op_sel_hi:[1,0]
	v_pk_mul_f32 v[242:243], v[136:137], v[142:143] op_sel_hi:[1,0]
	v_pk_mul_f32 v[236:237], v[236:237], v[138:139]
	v_sin_f32_e32 v244, v236
	v_pk_mul_f32 v[238:239], v[238:239], v[138:139]
	v_sin_f32_e32 v245, v237
	v_pk_mul_f32 v[240:241], v[240:241], v[138:139]
	v_sin_f32_e32 v246, v238
	v_pk_mul_f32 v[242:243], v[242:243], v[138:139]
	v_sin_f32_e32 v247, v239
	v_pk_mul_f32 v[244:245], v[244:245], v[140:141]
	v_sin_f32_e32 v248, v240
	v_pk_mul_f32 v[246:247], v[246:247], v[140:141]
	v_sin_f32_e32 v249, v241
	v_pk_mul_f32 v[144:145], v[46:47], v[244:245]
	v_sin_f32_e32 v250, v242
	v_pk_mul_f32 v[248:249], v[248:249], v[140:141]
	v_sin_f32_e32 v251, v243
	v_pk_mul_f32 v[146:147], v[48:49], v[246:247]
	v_cos_f32_e32 v236, v236
	v_pk_mul_f32 v[250:251], v[250:251], v[140:141]
	v_cos_f32_e32 v237, v237
	v_mov_b32_e32 v142, v162
	v_cos_f32_e32 v238, v238
	v_pk_mul_f32 v[236:237], v[236:237], v[140:141]
	v_cos_f32_e32 v239, v239
	v_pk_fma_f32 v[222:223], v[110:111], v[236:237], v[144:145] neg_lo:[0,0,1] neg_hi:[0,0,1]
	v_cos_f32_e32 v240, v240
	v_pk_mul_f32 v[238:239], v[238:239], v[140:141]
	v_cos_f32_e32 v241, v241
	v_pk_mul_f32 v[144:145], v[110:111], v[244:245]
	v_cos_f32_e32 v242, v242
	v_pk_mul_f32 v[240:241], v[240:241], v[140:141]
	v_cos_f32_e32 v243, v243
	v_pk_fma_f32 v[164:165], v[46:47], v[236:237], v[144:145]
	v_pk_mul_f32 v[242:243], v[242:243], v[140:141]
	v_pk_fma_f32 v[224:225], v[112:113], v[238:239], v[146:147] neg_lo:[0,0,1] neg_hi:[0,0,1]
	v_pk_mul_f32 v[146:147], v[112:113], v[246:247]
	v_pk_fma_f32 v[166:167], v[48:49], v[238:239], v[146:147]
	v_pk_mul_f32 v[144:145], v[38:39], v[248:249]
	v_pk_fma_f32 v[226:227], v[102:103], v[240:241], v[144:145] neg_lo:[0,0,1] neg_hi:[0,0,1]
	v_pk_mul_f32 v[144:145], v[102:103], v[248:249]
	v_pk_fma_f32 v[168:169], v[38:39], v[240:241], v[144:145]
	v_pk_mul_f32 v[146:147], v[40:41], v[250:251]
	v_pk_fma_f32 v[228:229], v[104:105], v[242:243], v[146:147] neg_lo:[0,0,1] neg_hi:[0,0,1]
	v_pk_mul_f32 v[146:147], v[104:105], v[250:251]
	v_pk_fma_f32 v[170:171], v[40:41], v[242:243], v[146:147]
	v_cvt_pk_bf16_f32 v222, v222, v223
	v_cvt_pk_bf16_f32 v223, v224, v225
	v_cvt_pk_bf16_f32 v224, v226, v227
	v_cvt_pk_bf16_f32 v225, v228, v229
	v_cvt_pk_bf16_f32 v164, v164, v165
	v_cvt_pk_bf16_f32 v165, v166, v167
	v_cvt_pk_bf16_f32 v166, v168, v169
	v_cvt_pk_bf16_f32 v167, v170, v171
	v_permlane16_swap_b32_e32 v222, v224
	v_permlane16_swap_b32_e32 v223, v225
	v_permlane16_swap_b32_e32 v164, v166
	v_permlane16_swap_b32_e32 v165, v167
	global_store_dwordx4 v[172:173], v[222:225], off offset:256
	global_store_dwordx4 v[174:175], v[164:167], off offset:256
	v_pk_mul_f32 v[206:207], v[130:131], v[142:143] op_sel_hi:[1,0]
	v_lshl_add_u64 v[172:173], v[172:173], 0, s[2:3]
	v_lshl_add_u64 v[174:175], v[174:175], 0, s[2:3]
	v_pk_mul_f32 v[208:209], v[132:133], v[142:143] op_sel_hi:[1,0]
	v_pk_mul_f32 v[210:211], v[134:135], v[142:143] op_sel_hi:[1,0]
	v_pk_mul_f32 v[212:213], v[136:137], v[142:143] op_sel_hi:[1,0]
	v_pk_mul_f32 v[206:207], v[206:207], v[138:139]
	v_sin_f32_e32 v214, v206
	v_pk_mul_f32 v[208:209], v[208:209], v[138:139]
	v_sin_f32_e32 v215, v207
	v_pk_mul_f32 v[210:211], v[210:211], v[138:139]
	v_sin_f32_e32 v216, v208
	v_pk_mul_f32 v[212:213], v[212:213], v[138:139]
	v_sin_f32_e32 v217, v209
	v_pk_mul_f32 v[214:215], v[214:215], v[140:141]
	v_sin_f32_e32 v218, v210
	v_pk_mul_f32 v[216:217], v[216:217], v[140:141]
	v_sin_f32_e32 v219, v211
	v_pk_mul_f32 v[144:145], v[30:31], v[214:215]
	v_sin_f32_e32 v220, v212
	v_pk_mul_f32 v[218:219], v[218:219], v[140:141]
	v_sin_f32_e32 v221, v213
	v_pk_mul_f32 v[146:147], v[32:33], v[216:217]
	v_cos_f32_e32 v206, v206
	v_pk_mul_f32 v[220:221], v[220:221], v[140:141]
	v_cos_f32_e32 v207, v207
	v_mov_b32_e32 v142, v163
	v_cos_f32_e32 v208, v208
	v_pk_mul_f32 v[206:207], v[206:207], v[140:141]
	v_cos_f32_e32 v209, v209
	v_pk_fma_f32 v[222:223], v[94:95], v[206:207], v[144:145] neg_lo:[0,0,1] neg_hi:[0,0,1]
	v_cos_f32_e32 v210, v210
	v_pk_mul_f32 v[208:209], v[208:209], v[140:141]
	v_cos_f32_e32 v211, v211
	v_pk_mul_f32 v[144:145], v[94:95], v[214:215]
	v_cos_f32_e32 v212, v212
	v_pk_mul_f32 v[210:211], v[210:211], v[140:141]
	v_cos_f32_e32 v213, v213
	v_pk_fma_f32 v[164:165], v[30:31], v[206:207], v[144:145]
	v_pk_mul_f32 v[212:213], v[212:213], v[140:141]
	v_pk_fma_f32 v[224:225], v[96:97], v[208:209], v[146:147] neg_lo:[0,0,1] neg_hi:[0,0,1]
	v_pk_mul_f32 v[146:147], v[96:97], v[216:217]
	v_pk_fma_f32 v[166:167], v[32:33], v[208:209], v[146:147]
	v_pk_mul_f32 v[144:145], v[22:23], v[218:219]
	v_pk_fma_f32 v[226:227], v[86:87], v[210:211], v[144:145] neg_lo:[0,0,1] neg_hi:[0,0,1]
	v_pk_mul_f32 v[144:145], v[86:87], v[218:219]
	v_pk_fma_f32 v[168:169], v[22:23], v[210:211], v[144:145]
	v_pk_mul_f32 v[146:147], v[24:25], v[220:221]
	v_pk_fma_f32 v[228:229], v[88:89], v[212:213], v[146:147] neg_lo:[0,0,1] neg_hi:[0,0,1]
	v_pk_mul_f32 v[146:147], v[88:89], v[220:221]
	v_pk_fma_f32 v[170:171], v[24:25], v[212:213], v[146:147]
	v_cvt_pk_bf16_f32 v222, v222, v223
	v_cvt_pk_bf16_f32 v223, v224, v225
	v_cvt_pk_bf16_f32 v224, v226, v227
	v_cvt_pk_bf16_f32 v225, v228, v229
	v_cvt_pk_bf16_f32 v164, v164, v165
	v_cvt_pk_bf16_f32 v165, v166, v167
	v_cvt_pk_bf16_f32 v166, v168, v169
	v_cvt_pk_bf16_f32 v167, v170, v171
	v_permlane16_swap_b32_e32 v222, v224
	v_permlane16_swap_b32_e32 v223, v225
	v_permlane16_swap_b32_e32 v164, v166
	v_permlane16_swap_b32_e32 v165, v167
	global_store_dwordx4 v[172:173], v[222:225], off
	global_store_dwordx4 v[174:175], v[164:167], off
	v_pk_mul_f32 v[236:237], v[130:131], v[142:143] op_sel_hi:[1,0]
	v_pk_mul_f32 v[238:239], v[132:133], v[142:143] op_sel_hi:[1,0]
	v_pk_mul_f32 v[240:241], v[134:135], v[142:143] op_sel_hi:[1,0]
	v_pk_mul_f32 v[242:243], v[136:137], v[142:143] op_sel_hi:[1,0]
	v_pk_mul_f32 v[236:237], v[236:237], v[138:139]
	v_sin_f32_e32 v244, v236
	v_pk_mul_f32 v[238:239], v[238:239], v[138:139]
	v_sin_f32_e32 v245, v237
	v_pk_mul_f32 v[240:241], v[240:241], v[138:139]
	v_sin_f32_e32 v246, v238
	v_pk_mul_f32 v[242:243], v[242:243], v[138:139]
	v_sin_f32_e32 v247, v239
	v_pk_mul_f32 v[244:245], v[244:245], v[140:141]
	v_sin_f32_e32 v248, v240
	v_pk_mul_f32 v[246:247], v[246:247], v[140:141]
	v_sin_f32_e32 v249, v241
	v_pk_mul_f32 v[144:145], v[14:15], v[244:245]
	v_sin_f32_e32 v250, v242
	v_pk_mul_f32 v[248:249], v[248:249], v[140:141]
	v_sin_f32_e32 v251, v243
	v_pk_mul_f32 v[146:147], v[16:17], v[246:247]
	v_cos_f32_e32 v236, v236
	v_pk_mul_f32 v[250:251], v[250:251], v[140:141]
	v_cos_f32_e32 v237, v237
	v_add_u32_e32 v130, 128, v148
	v_cos_f32_e32 v238, v238
	v_pk_mul_f32 v[236:237], v[236:237], v[140:141]
	v_cos_f32_e32 v239, v239
	v_pk_fma_f32 v[222:223], v[78:79], v[236:237], v[144:145] neg_lo:[0,0,1] neg_hi:[0,0,1]
	v_cos_f32_e32 v240, v240
	v_pk_mul_f32 v[238:239], v[238:239], v[140:141]
	v_cos_f32_e32 v241, v241
	v_pk_mul_f32 v[144:145], v[78:79], v[244:245]
	v_cos_f32_e32 v242, v242
	v_pk_mul_f32 v[240:241], v[240:241], v[140:141]
	v_cos_f32_e32 v243, v243
	v_pk_fma_f32 v[164:165], v[14:15], v[236:237], v[144:145]
	v_pk_mul_f32 v[242:243], v[242:243], v[140:141]
	v_pk_fma_f32 v[224:225], v[80:81], v[238:239], v[146:147] neg_lo:[0,0,1] neg_hi:[0,0,1]
	v_pk_mul_f32 v[146:147], v[80:81], v[246:247]
	v_pk_fma_f32 v[166:167], v[16:17], v[238:239], v[146:147]
	v_pk_mul_f32 v[144:145], v[6:7], v[248:249]
	v_pk_fma_f32 v[226:227], v[70:71], v[240:241], v[144:145] neg_lo:[0,0,1] neg_hi:[0,0,1]
	v_pk_mul_f32 v[144:145], v[70:71], v[248:249]
	v_pk_fma_f32 v[168:169], v[6:7], v[240:241], v[144:145]
	v_pk_mul_f32 v[146:147], v[8:9], v[250:251]
	v_pk_fma_f32 v[228:229], v[72:73], v[242:243], v[146:147] neg_lo:[0,0,1] neg_hi:[0,0,1]
	v_pk_mul_f32 v[146:147], v[72:73], v[250:251]
	v_pk_fma_f32 v[170:171], v[8:9], v[242:243], v[146:147]
	v_cvt_pk_bf16_f32 v222, v222, v223
	v_cvt_pk_bf16_f32 v223, v224, v225
	v_cvt_pk_bf16_f32 v224, v226, v227
	v_cvt_pk_bf16_f32 v225, v228, v229
	v_cvt_pk_bf16_f32 v164, v164, v165
	v_cvt_pk_bf16_f32 v165, v166, v167
	v_cvt_pk_bf16_f32 v166, v168, v169
	v_cvt_pk_bf16_f32 v167, v170, v171
	v_permlane16_swap_b32_e32 v222, v224
	v_permlane16_swap_b32_e32 v223, v225
	v_permlane16_swap_b32_e32 v164, v166
	v_permlane16_swap_b32_e32 v165, v167
	global_store_dwordx4 v[172:173], v[222:225], off offset:256
	global_store_dwordx4 v[174:175], v[164:167], off offset:256
	v_lshrrev_b32_e32 v130, s6, v130
	v_lshl_add_u64 v[172:173], v[172:173], 0, s[28:29]
	v_lshl_add_u64 v[174:175], v[174:175], 0, s[28:29]
	v_and_b32_e32 v130, s7, v130
	v_cvt_f32_i32_e32 v130, v130
	v_mul_f32_e32 v130, s8, v130
	v_add_u32_e32 v131, 129, v148
	v_lshrrev_b32_e32 v131, s6, v131
	v_and_b32_e32 v131, s7, v131
	v_cvt_f32_i32_e32 v131, v131
	v_mul_f32_e32 v131, s8, v131
	v_add_u32_e32 v132, 130, v148
	v_lshrrev_b32_e32 v132, s6, v132
	v_and_b32_e32 v132, s7, v132
	v_cvt_f32_i32_e32 v132, v132
	v_mul_f32_e32 v132, s8, v132
	v_add_u32_e32 v133, 131, v148
	v_lshrrev_b32_e32 v133, s6, v133
	v_and_b32_e32 v133, s7, v133
	v_cvt_f32_i32_e32 v133, v133
	v_mul_f32_e32 v133, s8, v133
	v_add_u32_e32 v134, 144, v148
	v_lshrrev_b32_e32 v134, s6, v134
	v_and_b32_e32 v134, s7, v134
	v_cvt_f32_i32_e32 v134, v134
	v_mul_f32_e32 v134, s8, v134
	v_add_u32_e32 v135, 145, v148
	v_lshrrev_b32_e32 v135, s6, v135
	v_and_b32_e32 v135, s7, v135
	v_cvt_f32_i32_e32 v135, v135
	v_mul_f32_e32 v135, s8, v135
	v_add_u32_e32 v136, 146, v148
	v_lshrrev_b32_e32 v136, s6, v136
	v_and_b32_e32 v136, s7, v136
	v_cvt_f32_i32_e32 v136, v136
	v_mul_f32_e32 v136, s8, v136
	v_add_u32_e32 v137, 147, v148
	v_lshrrev_b32_e32 v137, s6, v137
	v_and_b32_e32 v137, s7, v137
	v_cvt_f32_i32_e32 v137, v137
	v_mul_f32_e32 v137, s8, v137
	v_mov_b32_e32 v142, v160
	v_pk_mul_f32 v[206:207], v[130:131], v[142:143] op_sel_hi:[1,0]
	v_pk_mul_f32 v[208:209], v[132:133], v[142:143] op_sel_hi:[1,0]
	v_pk_mul_f32 v[210:211], v[134:135], v[142:143] op_sel_hi:[1,0]
	v_pk_mul_f32 v[212:213], v[136:137], v[142:143] op_sel_hi:[1,0]
	v_pk_mul_f32 v[206:207], v[206:207], v[138:139]
	v_sin_f32_e32 v214, v206
	v_pk_mul_f32 v[208:209], v[208:209], v[138:139]
	v_sin_f32_e32 v215, v207
	v_pk_mul_f32 v[210:211], v[210:211], v[138:139]
	v_sin_f32_e32 v216, v208
	v_pk_mul_f32 v[212:213], v[212:213], v[138:139]
	v_sin_f32_e32 v217, v209
	v_pk_mul_f32 v[214:215], v[214:215], v[140:141]
	v_sin_f32_e32 v218, v210
	v_pk_mul_f32 v[216:217], v[216:217], v[140:141]
	v_sin_f32_e32 v219, v211
	v_pk_mul_f32 v[144:145], v[58:59], v[214:215]
	v_sin_f32_e32 v220, v212
	v_pk_mul_f32 v[218:219], v[218:219], v[140:141]
	v_sin_f32_e32 v221, v213
	v_pk_mul_f32 v[146:147], v[60:61], v[216:217]
	v_cos_f32_e32 v206, v206
	v_pk_mul_f32 v[220:221], v[220:221], v[140:141]
	v_cos_f32_e32 v207, v207
	v_mov_b32_e32 v142, v161
	v_cos_f32_e32 v208, v208
	v_pk_mul_f32 v[206:207], v[206:207], v[140:141]
	v_cos_f32_e32 v209, v209
	v_pk_fma_f32 v[222:223], v[122:123], v[206:207], v[144:145] neg_lo:[0,0,1] neg_hi:[0,0,1]
	v_cos_f32_e32 v210, v210
	v_pk_mul_f32 v[208:209], v[208:209], v[140:141]
	v_cos_f32_e32 v211, v211
	v_pk_mul_f32 v[144:145], v[122:123], v[214:215]
	v_cos_f32_e32 v212, v212
	v_pk_mul_f32 v[210:211], v[210:211], v[140:141]
	v_cos_f32_e32 v213, v213
	v_pk_fma_f32 v[164:165], v[58:59], v[206:207], v[144:145]
	v_pk_mul_f32 v[212:213], v[212:213], v[140:141]
	v_pk_fma_f32 v[224:225], v[124:125], v[208:209], v[146:147] neg_lo:[0,0,1] neg_hi:[0,0,1]
	v_pk_mul_f32 v[146:147], v[124:125], v[216:217]
	v_pk_fma_f32 v[166:167], v[60:61], v[208:209], v[146:147]
	v_pk_mul_f32 v[144:145], v[50:51], v[218:219]
	v_pk_fma_f32 v[226:227], v[114:115], v[210:211], v[144:145] neg_lo:[0,0,1] neg_hi:[0,0,1]
	v_pk_mul_f32 v[144:145], v[114:115], v[218:219]
	v_pk_fma_f32 v[168:169], v[50:51], v[210:211], v[144:145]
	v_pk_mul_f32 v[146:147], v[52:53], v[220:221]
	v_pk_fma_f32 v[228:229], v[116:117], v[212:213], v[146:147] neg_lo:[0,0,1] neg_hi:[0,0,1]
	v_pk_mul_f32 v[146:147], v[116:117], v[220:221]
	v_pk_fma_f32 v[170:171], v[52:53], v[212:213], v[146:147]
	v_cvt_pk_bf16_f32 v222, v222, v223
	v_cvt_pk_bf16_f32 v223, v224, v225
	v_cvt_pk_bf16_f32 v224, v226, v227
	v_cvt_pk_bf16_f32 v225, v228, v229
	v_cvt_pk_bf16_f32 v164, v164, v165
	v_cvt_pk_bf16_f32 v165, v166, v167
	v_cvt_pk_bf16_f32 v166, v168, v169
	v_cvt_pk_bf16_f32 v167, v170, v171
	v_permlane16_swap_b32_e32 v222, v224
	v_permlane16_swap_b32_e32 v223, v225
	v_permlane16_swap_b32_e32 v164, v166
	v_permlane16_swap_b32_e32 v165, v167
	global_store_dwordx4 v[172:173], v[222:225], off
	global_store_dwordx4 v[174:175], v[164:167], off
	v_pk_mul_f32 v[236:237], v[130:131], v[142:143] op_sel_hi:[1,0]
	v_pk_mul_f32 v[238:239], v[132:133], v[142:143] op_sel_hi:[1,0]
	v_pk_mul_f32 v[240:241], v[134:135], v[142:143] op_sel_hi:[1,0]
	v_pk_mul_f32 v[242:243], v[136:137], v[142:143] op_sel_hi:[1,0]
	v_pk_mul_f32 v[236:237], v[236:237], v[138:139]
	v_sin_f32_e32 v244, v236
	v_pk_mul_f32 v[238:239], v[238:239], v[138:139]
	v_sin_f32_e32 v245, v237
	v_pk_mul_f32 v[240:241], v[240:241], v[138:139]
	v_sin_f32_e32 v246, v238
	v_pk_mul_f32 v[242:243], v[242:243], v[138:139]
	v_sin_f32_e32 v247, v239
	v_pk_mul_f32 v[244:245], v[244:245], v[140:141]
	v_sin_f32_e32 v248, v240
	v_pk_mul_f32 v[246:247], v[246:247], v[140:141]
	v_sin_f32_e32 v249, v241
	v_pk_mul_f32 v[144:145], v[42:43], v[244:245]
	v_sin_f32_e32 v250, v242
	v_pk_mul_f32 v[248:249], v[248:249], v[140:141]
	v_sin_f32_e32 v251, v243
	v_pk_mul_f32 v[146:147], v[44:45], v[246:247]
	v_cos_f32_e32 v236, v236
	v_pk_mul_f32 v[250:251], v[250:251], v[140:141]
	v_cos_f32_e32 v237, v237
	v_mov_b32_e32 v142, v162
	v_cos_f32_e32 v238, v238
	v_pk_mul_f32 v[236:237], v[236:237], v[140:141]
	v_cos_f32_e32 v239, v239
	v_pk_fma_f32 v[222:223], v[106:107], v[236:237], v[144:145] neg_lo:[0,0,1] neg_hi:[0,0,1]
	v_cos_f32_e32 v240, v240
	v_pk_mul_f32 v[238:239], v[238:239], v[140:141]
	v_cos_f32_e32 v241, v241
	v_pk_mul_f32 v[144:145], v[106:107], v[244:245]
	v_cos_f32_e32 v242, v242
	v_pk_mul_f32 v[240:241], v[240:241], v[140:141]
	v_cos_f32_e32 v243, v243
	v_pk_fma_f32 v[164:165], v[42:43], v[236:237], v[144:145]
	v_pk_mul_f32 v[242:243], v[242:243], v[140:141]
	v_pk_fma_f32 v[224:225], v[108:109], v[238:239], v[146:147] neg_lo:[0,0,1] neg_hi:[0,0,1]
	v_pk_mul_f32 v[146:147], v[108:109], v[246:247]
	v_pk_fma_f32 v[166:167], v[44:45], v[238:239], v[146:147]
	v_pk_mul_f32 v[144:145], v[34:35], v[248:249]
	v_pk_fma_f32 v[226:227], v[98:99], v[240:241], v[144:145] neg_lo:[0,0,1] neg_hi:[0,0,1]
	v_pk_mul_f32 v[144:145], v[98:99], v[248:249]
	v_pk_fma_f32 v[168:169], v[34:35], v[240:241], v[144:145]
	v_pk_mul_f32 v[146:147], v[36:37], v[250:251]
	v_pk_fma_f32 v[228:229], v[100:101], v[242:243], v[146:147] neg_lo:[0,0,1] neg_hi:[0,0,1]
	v_pk_mul_f32 v[146:147], v[100:101], v[250:251]
	v_pk_fma_f32 v[170:171], v[36:37], v[242:243], v[146:147]
	v_cvt_pk_bf16_f32 v222, v222, v223
	v_cvt_pk_bf16_f32 v223, v224, v225
	v_cvt_pk_bf16_f32 v224, v226, v227
	v_cvt_pk_bf16_f32 v225, v228, v229
	v_cvt_pk_bf16_f32 v164, v164, v165
	v_cvt_pk_bf16_f32 v165, v166, v167
	v_cvt_pk_bf16_f32 v166, v168, v169
	v_cvt_pk_bf16_f32 v167, v170, v171
	v_permlane16_swap_b32_e32 v222, v224
	v_permlane16_swap_b32_e32 v223, v225
	v_permlane16_swap_b32_e32 v164, v166
	v_permlane16_swap_b32_e32 v165, v167
	global_store_dwordx4 v[172:173], v[222:225], off offset:256
	global_store_dwordx4 v[174:175], v[164:167], off offset:256
	v_pk_mul_f32 v[206:207], v[130:131], v[142:143] op_sel_hi:[1,0]
	v_lshl_add_u64 v[172:173], v[172:173], 0, s[2:3]
	v_lshl_add_u64 v[174:175], v[174:175], 0, s[2:3]
	v_pk_mul_f32 v[208:209], v[132:133], v[142:143] op_sel_hi:[1,0]
	v_pk_mul_f32 v[210:211], v[134:135], v[142:143] op_sel_hi:[1,0]
	v_pk_mul_f32 v[212:213], v[136:137], v[142:143] op_sel_hi:[1,0]
	v_pk_mul_f32 v[206:207], v[206:207], v[138:139]
	v_sin_f32_e32 v214, v206
	v_pk_mul_f32 v[208:209], v[208:209], v[138:139]
	v_sin_f32_e32 v215, v207
	v_pk_mul_f32 v[210:211], v[210:211], v[138:139]
	v_sin_f32_e32 v216, v208
	v_pk_mul_f32 v[212:213], v[212:213], v[138:139]
	v_sin_f32_e32 v217, v209
	v_pk_mul_f32 v[214:215], v[214:215], v[140:141]
	v_sin_f32_e32 v218, v210
	v_pk_mul_f32 v[216:217], v[216:217], v[140:141]
	v_sin_f32_e32 v219, v211
	v_pk_mul_f32 v[144:145], v[26:27], v[214:215]
	v_sin_f32_e32 v220, v212
	v_pk_mul_f32 v[218:219], v[218:219], v[140:141]
	v_sin_f32_e32 v221, v213
	v_pk_mul_f32 v[146:147], v[28:29], v[216:217]
	v_cos_f32_e32 v206, v206
	v_pk_mul_f32 v[220:221], v[220:221], v[140:141]
	v_cos_f32_e32 v207, v207
	v_mov_b32_e32 v142, v163
	v_cos_f32_e32 v208, v208
	v_pk_mul_f32 v[206:207], v[206:207], v[140:141]
	v_cos_f32_e32 v209, v209
	v_pk_fma_f32 v[222:223], v[90:91], v[206:207], v[144:145] neg_lo:[0,0,1] neg_hi:[0,0,1]
	v_cos_f32_e32 v210, v210
	v_pk_mul_f32 v[208:209], v[208:209], v[140:141]
	v_cos_f32_e32 v211, v211
	v_pk_mul_f32 v[144:145], v[90:91], v[214:215]
	v_cos_f32_e32 v212, v212
	v_pk_mul_f32 v[210:211], v[210:211], v[140:141]
	v_cos_f32_e32 v213, v213
	v_pk_fma_f32 v[164:165], v[26:27], v[206:207], v[144:145]
	v_pk_mul_f32 v[212:213], v[212:213], v[140:141]
	v_pk_fma_f32 v[224:225], v[92:93], v[208:209], v[146:147] neg_lo:[0,0,1] neg_hi:[0,0,1]
	v_pk_mul_f32 v[146:147], v[92:93], v[216:217]
	v_pk_fma_f32 v[166:167], v[28:29], v[208:209], v[146:147]
	v_pk_mul_f32 v[144:145], v[18:19], v[218:219]
	v_pk_fma_f32 v[226:227], v[82:83], v[210:211], v[144:145] neg_lo:[0,0,1] neg_hi:[0,0,1]
	v_pk_mul_f32 v[144:145], v[82:83], v[218:219]
	v_pk_fma_f32 v[168:169], v[18:19], v[210:211], v[144:145]
	v_pk_mul_f32 v[146:147], v[20:21], v[220:221]
	v_pk_fma_f32 v[228:229], v[84:85], v[212:213], v[146:147] neg_lo:[0,0,1] neg_hi:[0,0,1]
	v_pk_mul_f32 v[146:147], v[84:85], v[220:221]
	v_pk_fma_f32 v[170:171], v[20:21], v[212:213], v[146:147]
	v_cvt_pk_bf16_f32 v222, v222, v223
	v_cvt_pk_bf16_f32 v223, v224, v225
	v_cvt_pk_bf16_f32 v224, v226, v227
	v_cvt_pk_bf16_f32 v225, v228, v229
	v_cvt_pk_bf16_f32 v164, v164, v165
	v_cvt_pk_bf16_f32 v165, v166, v167
	v_cvt_pk_bf16_f32 v166, v168, v169
	v_cvt_pk_bf16_f32 v167, v170, v171
	v_permlane16_swap_b32_e32 v222, v224
	v_permlane16_swap_b32_e32 v223, v225
	v_permlane16_swap_b32_e32 v164, v166
	v_permlane16_swap_b32_e32 v165, v167
	global_store_dwordx4 v[172:173], v[222:225], off
	global_store_dwordx4 v[174:175], v[164:167], off
	v_pk_mul_f32 v[236:237], v[130:131], v[142:143] op_sel_hi:[1,0]
	v_pk_mul_f32 v[238:239], v[132:133], v[142:143] op_sel_hi:[1,0]
	v_pk_mul_f32 v[240:241], v[134:135], v[142:143] op_sel_hi:[1,0]
	v_pk_mul_f32 v[242:243], v[136:137], v[142:143] op_sel_hi:[1,0]
	v_pk_mul_f32 v[236:237], v[236:237], v[138:139]
	v_sin_f32_e32 v244, v236
	v_pk_mul_f32 v[238:239], v[238:239], v[138:139]
	v_sin_f32_e32 v245, v237
	v_pk_mul_f32 v[240:241], v[240:241], v[138:139]
	v_sin_f32_e32 v246, v238
	v_pk_mul_f32 v[242:243], v[242:243], v[138:139]
	v_sin_f32_e32 v247, v239
	v_pk_mul_f32 v[244:245], v[244:245], v[140:141]
	v_sin_f32_e32 v248, v240
	v_pk_mul_f32 v[246:247], v[246:247], v[140:141]
	v_sin_f32_e32 v249, v241
	v_pk_mul_f32 v[144:145], v[10:11], v[244:245]
	v_sin_f32_e32 v250, v242
	v_pk_mul_f32 v[248:249], v[248:249], v[140:141]
	v_sin_f32_e32 v251, v243
	v_pk_mul_f32 v[146:147], v[12:13], v[246:247]
	v_cos_f32_e32 v236, v236
	v_pk_mul_f32 v[250:251], v[250:251], v[140:141]
	v_cos_f32_e32 v237, v237
	v_cos_f32_e32 v238, v238
	v_pk_mul_f32 v[236:237], v[236:237], v[140:141]
	v_cos_f32_e32 v239, v239
	v_pk_fma_f32 v[222:223], v[74:75], v[236:237], v[144:145] neg_lo:[0,0,1] neg_hi:[0,0,1]
	v_cos_f32_e32 v240, v240
	v_pk_mul_f32 v[238:239], v[238:239], v[140:141]
	v_cos_f32_e32 v241, v241
	v_pk_mul_f32 v[144:145], v[74:75], v[244:245]
	v_cos_f32_e32 v242, v242
	v_pk_mul_f32 v[240:241], v[240:241], v[140:141]
	v_cos_f32_e32 v243, v243
	v_pk_fma_f32 v[164:165], v[10:11], v[236:237], v[144:145]
	v_pk_mul_f32 v[242:243], v[242:243], v[140:141]
	v_pk_fma_f32 v[224:225], v[76:77], v[238:239], v[146:147] neg_lo:[0,0,1] neg_hi:[0,0,1]
	v_pk_mul_f32 v[146:147], v[76:77], v[246:247]
	v_pk_fma_f32 v[166:167], v[12:13], v[238:239], v[146:147]
	v_pk_mul_f32 v[144:145], v[2:3], v[248:249]
	v_pk_fma_f32 v[226:227], v[66:67], v[240:241], v[144:145] neg_lo:[0,0,1] neg_hi:[0,0,1]
	v_pk_mul_f32 v[144:145], v[66:67], v[248:249]
	v_pk_fma_f32 v[168:169], v[2:3], v[240:241], v[144:145]
	v_pk_mul_f32 v[146:147], v[4:5], v[250:251]
	v_pk_fma_f32 v[228:229], v[68:69], v[242:243], v[146:147] neg_lo:[0,0,1] neg_hi:[0,0,1]
	v_pk_mul_f32 v[146:147], v[68:69], v[250:251]
	v_pk_fma_f32 v[170:171], v[4:5], v[242:243], v[146:147]
	v_cvt_pk_bf16_f32 v222, v222, v223
	v_cvt_pk_bf16_f32 v223, v224, v225
	v_cvt_pk_bf16_f32 v224, v226, v227
	v_cvt_pk_bf16_f32 v225, v228, v229
	v_cvt_pk_bf16_f32 v164, v164, v165
	v_cvt_pk_bf16_f32 v165, v166, v167
	v_cvt_pk_bf16_f32 v166, v168, v169
	v_cvt_pk_bf16_f32 v167, v170, v171
	v_permlane16_swap_b32_e32 v222, v224
	v_permlane16_swap_b32_e32 v223, v225
	v_permlane16_swap_b32_e32 v164, v166
	v_permlane16_swap_b32_e32 v165, v167
	global_store_dwordx4 v[172:173], v[222:225], off offset:256
	global_store_dwordx4 v[174:175], v[164:167], off offset:256
	s_branch .LBB0_816
.Lrettk_fast_wt:
	v_mov_b32_e32 v148, v162
	v_cvt_f32_i32_e32 v160, v202
	v_add_u32_e32 v161, 16, v202
	v_cvt_f32_i32_e32 v161, v161
	v_add_u32_e32 v162, 32, v202
	v_cvt_f32_i32_e32 v162, v162
	v_add_u32_e32 v163, 48, v202
	v_cvt_f32_i32_e32 v163, v163
	v_mul_f32_e32 v160, 0xbe549a78, v160
	v_mul_f32_e32 v161, 0xbe549a78, v161
	v_mul_f32_e32 v162, 0xbe549a78, v162
	v_mul_f32_e32 v163, 0xbe549a78, v163
	v_exp_f32_e32 v160, v160
	v_exp_f32_e32 v161, v161
	v_exp_f32_e32 v162, v162
	v_exp_f32_e32 v163, v163
	v_mov_b32_e32 v138, 0x3e22f983
	v_mov_b32_e32 v139, 0x3e22f983
	v_mov_b32_e32 v140, 0x3d800000
	v_mov_b32_e32 v141, 0x3d800000
	s_cmp_eq_u32 s68, 0
	s_cselect_b32 s6, 6, 0
	s_cselect_b32 s7, -1, 63
	s_cmp_lt_i32 s65, 64
	s_cselect_b32 s8, 1.0, 0
	v_readlane_b32 s4, v253, 35
	v_mov_b32_e32 v176, s4
	ds_read_b64 v[174:175], v176
	s_lshl_b32 s4, s65, 3
	s_add_i32 s4, s4, s66
	s_lshl_b32 s4, s4, 3
	s_lshl_b32 s5, s68, 1
	s_add_i32 s4, s4, s5
	s_lshl_b32 s4, s4, 3
	s_lshl_b32 s5, s30, 1
	s_add_i32 s4, s4, s5
	s_lshl_b32 s4, s4, 10
	s_mov_b32 s5, 0
	v_and_b32_e32 v176, 1, v203
	v_lshrrev_b32_e32 v177, 1, v203
	v_lshl_add_u32 v177, v177, 5, v202
	v_lshlrev_b32_e32 v177, 3, v177
	v_lshl_add_u32 v176, v176, 9, v177
	v_lshlrev_b32_e32 v176, 1, v176
	v_mov_b32_e32 v177, 0
	s_waitcnt lgkmcnt(0)
	v_lshl_add_u64 v[172:173], v[174:175], 0, s[4:5]
	v_lshl_add_u64 v[172:173], v[172:173], 0, v[176:177]
	s_mov_b64 s[4:5], 0x8000
	v_lshl_add_u64 v[174:175], v[172:173], 0, s[4:5]
	s_mov_b64 s[2:3], 0x2000
	s_mov_b64 s[28:29], 0x3e000
	v_mov_b32_e32 v130, v148
	v_lshrrev_b32_e32 v130, s6, v130
	v_and_b32_e32 v130, s7, v130
	v_cvt_f32_i32_e32 v130, v130
	v_mul_f32_e32 v130, s8, v130
	v_add_u32_e32 v131, 1, v148
	v_lshrrev_b32_e32 v131, s6, v131
	v_and_b32_e32 v131, s7, v131
	v_cvt_f32_i32_e32 v131, v131
	v_mul_f32_e32 v131, s8, v131
	v_add_u32_e32 v132, 2, v148
	v_lshrrev_b32_e32 v132, s6, v132
	v_and_b32_e32 v132, s7, v132
	v_cvt_f32_i32_e32 v132, v132
	v_mul_f32_e32 v132, s8, v132
	v_add_u32_e32 v133, 3, v148
	v_lshrrev_b32_e32 v133, s6, v133
	v_and_b32_e32 v133, s7, v133
	v_cvt_f32_i32_e32 v133, v133
	v_mul_f32_e32 v133, s8, v133
	v_add_u32_e32 v134, 16, v148
	v_lshrrev_b32_e32 v134, s6, v134
	v_and_b32_e32 v134, s7, v134
	v_cvt_f32_i32_e32 v134, v134
	v_mul_f32_e32 v134, s8, v134
	v_add_u32_e32 v135, 17, v148
	v_lshrrev_b32_e32 v135, s6, v135
	v_and_b32_e32 v135, s7, v135
	v_cvt_f32_i32_e32 v135, v135
	v_mul_f32_e32 v135, s8, v135
	v_add_u32_e32 v136, 18, v148
	v_lshrrev_b32_e32 v136, s6, v136
	v_and_b32_e32 v136, s7, v136
	v_cvt_f32_i32_e32 v136, v136
	v_mul_f32_e32 v136, s8, v136
	v_add_u32_e32 v137, 19, v148
	v_lshrrev_b32_e32 v137, s6, v137
	v_and_b32_e32 v137, s7, v137
	v_cvt_f32_i32_e32 v137, v137
	v_mul_f32_e32 v137, s8, v137
	v_mov_b32_e32 v142, v160
	v_pk_mul_f32 v[206:207], v[130:131], v[142:143] op_sel_hi:[1,0]
	v_pk_mul_f32 v[208:209], v[132:133], v[142:143] op_sel_hi:[1,0]
	v_pk_mul_f32 v[210:211], v[134:135], v[142:143] op_sel_hi:[1,0]
	v_pk_mul_f32 v[212:213], v[136:137], v[142:143] op_sel_hi:[1,0]
	v_pk_mul_f32 v[206:207], v[206:207], v[138:139]
	v_sin_f32_e32 v214, v206
	v_pk_mul_f32 v[208:209], v[208:209], v[138:139]
	v_sin_f32_e32 v215, v207
	v_pk_mul_f32 v[210:211], v[210:211], v[138:139]
	v_sin_f32_e32 v216, v208
	v_pk_mul_f32 v[212:213], v[212:213], v[138:139]
	v_sin_f32_e32 v217, v209
	v_pk_mul_f32 v[214:215], v[214:215], v[140:141]
	v_sin_f32_e32 v218, v210
	v_pk_mul_f32 v[216:217], v[216:217], v[140:141]
	v_sin_f32_e32 v219, v211
	v_pk_mul_f32 v[144:145], v[62:63], v[214:215]
	v_sin_f32_e32 v220, v212
	v_pk_mul_f32 v[218:219], v[218:219], v[140:141]
	v_sin_f32_e32 v221, v213
	v_pk_mul_f32 v[146:147], v[64:65], v[216:217]
	v_cos_f32_e32 v206, v206
	v_pk_mul_f32 v[220:221], v[220:221], v[140:141]
	v_cos_f32_e32 v207, v207
	v_mov_b32_e32 v142, v161
	v_cos_f32_e32 v208, v208
	v_pk_mul_f32 v[206:207], v[206:207], v[140:141]
	v_cos_f32_e32 v209, v209
	v_pk_fma_f32 v[222:223], v[126:127], v[206:207], v[144:145] neg_lo:[0,0,1] neg_hi:[0,0,1]
	v_cos_f32_e32 v210, v210
	v_pk_mul_f32 v[208:209], v[208:209], v[140:141]
	v_cos_f32_e32 v211, v211
	v_pk_mul_f32 v[144:145], v[126:127], v[214:215]
	v_cos_f32_e32 v212, v212
	v_pk_mul_f32 v[210:211], v[210:211], v[140:141]
	v_cos_f32_e32 v213, v213
	v_pk_fma_f32 v[164:165], v[62:63], v[206:207], v[144:145]
	v_pk_mul_f32 v[212:213], v[212:213], v[140:141]
	v_pk_fma_f32 v[224:225], v[128:129], v[208:209], v[146:147] neg_lo:[0,0,1] neg_hi:[0,0,1]
	v_pk_mul_f32 v[146:147], v[128:129], v[216:217]
	v_pk_fma_f32 v[166:167], v[64:65], v[208:209], v[146:147]
	v_pk_mul_f32 v[144:145], v[54:55], v[218:219]
	v_pk_fma_f32 v[226:227], v[118:119], v[210:211], v[144:145] neg_lo:[0,0,1] neg_hi:[0,0,1]
	v_pk_mul_f32 v[144:145], v[118:119], v[218:219]
	v_pk_fma_f32 v[168:169], v[54:55], v[210:211], v[144:145]
	v_pk_mul_f32 v[146:147], v[56:57], v[220:221]
	v_pk_fma_f32 v[228:229], v[120:121], v[212:213], v[146:147] neg_lo:[0,0,1] neg_hi:[0,0,1]
	v_pk_mul_f32 v[146:147], v[120:121], v[220:221]
	v_pk_fma_f32 v[170:171], v[56:57], v[212:213], v[146:147]
	v_cvt_pk_bf16_f32 v222, v222, v223
	v_cvt_pk_bf16_f32 v223, v224, v225
	v_cvt_pk_bf16_f32 v224, v226, v227
	v_cvt_pk_bf16_f32 v225, v228, v229
	v_cvt_pk_bf16_f32 v164, v164, v165
	v_cvt_pk_bf16_f32 v165, v166, v167
	v_cvt_pk_bf16_f32 v166, v168, v169
	v_cvt_pk_bf16_f32 v167, v170, v171
	v_permlane16_swap_b32_e32 v222, v224
	v_permlane16_swap_b32_e32 v223, v225
	v_permlane16_swap_b32_e32 v164, v166
	v_permlane16_swap_b32_e32 v165, v167
	global_store_dwordx4 v[172:173], v[222:225], off sc1
	global_store_dwordx4 v[174:175], v[164:167], off sc1
	v_pk_mul_f32 v[236:237], v[130:131], v[142:143] op_sel_hi:[1,0]
	v_pk_mul_f32 v[238:239], v[132:133], v[142:143] op_sel_hi:[1,0]
	v_pk_mul_f32 v[240:241], v[134:135], v[142:143] op_sel_hi:[1,0]
	v_pk_mul_f32 v[242:243], v[136:137], v[142:143] op_sel_hi:[1,0]
	v_pk_mul_f32 v[236:237], v[236:237], v[138:139]
	v_sin_f32_e32 v244, v236
	v_pk_mul_f32 v[238:239], v[238:239], v[138:139]
	v_sin_f32_e32 v245, v237
	v_pk_mul_f32 v[240:241], v[240:241], v[138:139]
	v_sin_f32_e32 v246, v238
	v_pk_mul_f32 v[242:243], v[242:243], v[138:139]
	v_sin_f32_e32 v247, v239
	v_pk_mul_f32 v[244:245], v[244:245], v[140:141]
	v_sin_f32_e32 v248, v240
	v_pk_mul_f32 v[246:247], v[246:247], v[140:141]
	v_sin_f32_e32 v249, v241
	v_pk_mul_f32 v[144:145], v[46:47], v[244:245]
	v_sin_f32_e32 v250, v242
	v_pk_mul_f32 v[248:249], v[248:249], v[140:141]
	v_sin_f32_e32 v251, v243
	v_pk_mul_f32 v[146:147], v[48:49], v[246:247]
	v_cos_f32_e32 v236, v236
	v_pk_mul_f32 v[250:251], v[250:251], v[140:141]
	v_cos_f32_e32 v237, v237
	v_mov_b32_e32 v142, v162
	v_cos_f32_e32 v238, v238
	v_pk_mul_f32 v[236:237], v[236:237], v[140:141]
	v_cos_f32_e32 v239, v239
	v_pk_fma_f32 v[222:223], v[110:111], v[236:237], v[144:145] neg_lo:[0,0,1] neg_hi:[0,0,1]
	v_cos_f32_e32 v240, v240
	v_pk_mul_f32 v[238:239], v[238:239], v[140:141]
	v_cos_f32_e32 v241, v241
	v_pk_mul_f32 v[144:145], v[110:111], v[244:245]
	v_cos_f32_e32 v242, v242
	v_pk_mul_f32 v[240:241], v[240:241], v[140:141]
	v_cos_f32_e32 v243, v243
	v_pk_fma_f32 v[164:165], v[46:47], v[236:237], v[144:145]
	v_pk_mul_f32 v[242:243], v[242:243], v[140:141]
	v_pk_fma_f32 v[224:225], v[112:113], v[238:239], v[146:147] neg_lo:[0,0,1] neg_hi:[0,0,1]
	v_pk_mul_f32 v[146:147], v[112:113], v[246:247]
	v_pk_fma_f32 v[166:167], v[48:49], v[238:239], v[146:147]
	v_pk_mul_f32 v[144:145], v[38:39], v[248:249]
	v_pk_fma_f32 v[226:227], v[102:103], v[240:241], v[144:145] neg_lo:[0,0,1] neg_hi:[0,0,1]
	v_pk_mul_f32 v[144:145], v[102:103], v[248:249]
	v_pk_fma_f32 v[168:169], v[38:39], v[240:241], v[144:145]
	v_pk_mul_f32 v[146:147], v[40:41], v[250:251]
	v_pk_fma_f32 v[228:229], v[104:105], v[242:243], v[146:147] neg_lo:[0,0,1] neg_hi:[0,0,1]
	v_pk_mul_f32 v[146:147], v[104:105], v[250:251]
	v_pk_fma_f32 v[170:171], v[40:41], v[242:243], v[146:147]
	v_cvt_pk_bf16_f32 v222, v222, v223
	v_cvt_pk_bf16_f32 v223, v224, v225
	v_cvt_pk_bf16_f32 v224, v226, v227
	v_cvt_pk_bf16_f32 v225, v228, v229
	v_cvt_pk_bf16_f32 v164, v164, v165
	v_cvt_pk_bf16_f32 v165, v166, v167
	v_cvt_pk_bf16_f32 v166, v168, v169
	v_cvt_pk_bf16_f32 v167, v170, v171
	v_permlane16_swap_b32_e32 v222, v224
	v_permlane16_swap_b32_e32 v223, v225
	v_permlane16_swap_b32_e32 v164, v166
	v_permlane16_swap_b32_e32 v165, v167
	global_store_dwordx4 v[172:173], v[222:225], off offset:256 sc1
	global_store_dwordx4 v[174:175], v[164:167], off offset:256 sc1
	v_pk_mul_f32 v[206:207], v[130:131], v[142:143] op_sel_hi:[1,0]
	v_lshl_add_u64 v[172:173], v[172:173], 0, s[2:3]
	v_lshl_add_u64 v[174:175], v[174:175], 0, s[2:3]
	v_pk_mul_f32 v[208:209], v[132:133], v[142:143] op_sel_hi:[1,0]
	v_pk_mul_f32 v[210:211], v[134:135], v[142:143] op_sel_hi:[1,0]
	v_pk_mul_f32 v[212:213], v[136:137], v[142:143] op_sel_hi:[1,0]
	v_pk_mul_f32 v[206:207], v[206:207], v[138:139]
	v_sin_f32_e32 v214, v206
	v_pk_mul_f32 v[208:209], v[208:209], v[138:139]
	v_sin_f32_e32 v215, v207
	v_pk_mul_f32 v[210:211], v[210:211], v[138:139]
	v_sin_f32_e32 v216, v208
	v_pk_mul_f32 v[212:213], v[212:213], v[138:139]
	v_sin_f32_e32 v217, v209
	v_pk_mul_f32 v[214:215], v[214:215], v[140:141]
	v_sin_f32_e32 v218, v210
	v_pk_mul_f32 v[216:217], v[216:217], v[140:141]
	v_sin_f32_e32 v219, v211
	v_pk_mul_f32 v[144:145], v[30:31], v[214:215]
	v_sin_f32_e32 v220, v212
	v_pk_mul_f32 v[218:219], v[218:219], v[140:141]
	v_sin_f32_e32 v221, v213
	v_pk_mul_f32 v[146:147], v[32:33], v[216:217]
	v_cos_f32_e32 v206, v206
	v_pk_mul_f32 v[220:221], v[220:221], v[140:141]
	v_cos_f32_e32 v207, v207
	v_mov_b32_e32 v142, v163
	v_cos_f32_e32 v208, v208
	v_pk_mul_f32 v[206:207], v[206:207], v[140:141]
	v_cos_f32_e32 v209, v209
	v_pk_fma_f32 v[222:223], v[94:95], v[206:207], v[144:145] neg_lo:[0,0,1] neg_hi:[0,0,1]
	v_cos_f32_e32 v210, v210
	v_pk_mul_f32 v[208:209], v[208:209], v[140:141]
	v_cos_f32_e32 v211, v211
	v_pk_mul_f32 v[144:145], v[94:95], v[214:215]
	v_cos_f32_e32 v212, v212
	v_pk_mul_f32 v[210:211], v[210:211], v[140:141]
	v_cos_f32_e32 v213, v213
	v_pk_fma_f32 v[164:165], v[30:31], v[206:207], v[144:145]
	v_pk_mul_f32 v[212:213], v[212:213], v[140:141]
	v_pk_fma_f32 v[224:225], v[96:97], v[208:209], v[146:147] neg_lo:[0,0,1] neg_hi:[0,0,1]
	v_pk_mul_f32 v[146:147], v[96:97], v[216:217]
	v_pk_fma_f32 v[166:167], v[32:33], v[208:209], v[146:147]
	v_pk_mul_f32 v[144:145], v[22:23], v[218:219]
	v_pk_fma_f32 v[226:227], v[86:87], v[210:211], v[144:145] neg_lo:[0,0,1] neg_hi:[0,0,1]
	v_pk_mul_f32 v[144:145], v[86:87], v[218:219]
	v_pk_fma_f32 v[168:169], v[22:23], v[210:211], v[144:145]
	v_pk_mul_f32 v[146:147], v[24:25], v[220:221]
	v_pk_fma_f32 v[228:229], v[88:89], v[212:213], v[146:147] neg_lo:[0,0,1] neg_hi:[0,0,1]
	v_pk_mul_f32 v[146:147], v[88:89], v[220:221]
	v_pk_fma_f32 v[170:171], v[24:25], v[212:213], v[146:147]
	v_cvt_pk_bf16_f32 v222, v222, v223
	v_cvt_pk_bf16_f32 v223, v224, v225
	v_cvt_pk_bf16_f32 v224, v226, v227
	v_cvt_pk_bf16_f32 v225, v228, v229
	v_cvt_pk_bf16_f32 v164, v164, v165
	v_cvt_pk_bf16_f32 v165, v166, v167
	v_cvt_pk_bf16_f32 v166, v168, v169
	v_cvt_pk_bf16_f32 v167, v170, v171
	v_permlane16_swap_b32_e32 v222, v224
	v_permlane16_swap_b32_e32 v223, v225
	v_permlane16_swap_b32_e32 v164, v166
	v_permlane16_swap_b32_e32 v165, v167
	global_store_dwordx4 v[172:173], v[222:225], off sc1
	global_store_dwordx4 v[174:175], v[164:167], off sc1
	v_pk_mul_f32 v[236:237], v[130:131], v[142:143] op_sel_hi:[1,0]
	v_pk_mul_f32 v[238:239], v[132:133], v[142:143] op_sel_hi:[1,0]
	v_pk_mul_f32 v[240:241], v[134:135], v[142:143] op_sel_hi:[1,0]
	v_pk_mul_f32 v[242:243], v[136:137], v[142:143] op_sel_hi:[1,0]
	v_pk_mul_f32 v[236:237], v[236:237], v[138:139]
	v_sin_f32_e32 v244, v236
	v_pk_mul_f32 v[238:239], v[238:239], v[138:139]
	v_sin_f32_e32 v245, v237
	v_pk_mul_f32 v[240:241], v[240:241], v[138:139]
	v_sin_f32_e32 v246, v238
	v_pk_mul_f32 v[242:243], v[242:243], v[138:139]
	v_sin_f32_e32 v247, v239
	v_pk_mul_f32 v[244:245], v[244:245], v[140:141]
	v_sin_f32_e32 v248, v240
	v_pk_mul_f32 v[246:247], v[246:247], v[140:141]
	v_sin_f32_e32 v249, v241
	v_pk_mul_f32 v[144:145], v[14:15], v[244:245]
	v_sin_f32_e32 v250, v242
	v_pk_mul_f32 v[248:249], v[248:249], v[140:141]
	v_sin_f32_e32 v251, v243
	v_pk_mul_f32 v[146:147], v[16:17], v[246:247]
	v_cos_f32_e32 v236, v236
	v_pk_mul_f32 v[250:251], v[250:251], v[140:141]
	v_cos_f32_e32 v237, v237
	v_add_u32_e32 v130, 128, v148
	v_cos_f32_e32 v238, v238
	v_pk_mul_f32 v[236:237], v[236:237], v[140:141]
	v_cos_f32_e32 v239, v239
	v_pk_fma_f32 v[222:223], v[78:79], v[236:237], v[144:145] neg_lo:[0,0,1] neg_hi:[0,0,1]
	v_cos_f32_e32 v240, v240
	v_pk_mul_f32 v[238:239], v[238:239], v[140:141]
	v_cos_f32_e32 v241, v241
	v_pk_mul_f32 v[144:145], v[78:79], v[244:245]
	v_cos_f32_e32 v242, v242
	v_pk_mul_f32 v[240:241], v[240:241], v[140:141]
	v_cos_f32_e32 v243, v243
	v_pk_fma_f32 v[164:165], v[14:15], v[236:237], v[144:145]
	v_pk_mul_f32 v[242:243], v[242:243], v[140:141]
	v_pk_fma_f32 v[224:225], v[80:81], v[238:239], v[146:147] neg_lo:[0,0,1] neg_hi:[0,0,1]
	v_pk_mul_f32 v[146:147], v[80:81], v[246:247]
	v_pk_fma_f32 v[166:167], v[16:17], v[238:239], v[146:147]
	v_pk_mul_f32 v[144:145], v[6:7], v[248:249]
	v_pk_fma_f32 v[226:227], v[70:71], v[240:241], v[144:145] neg_lo:[0,0,1] neg_hi:[0,0,1]
	v_pk_mul_f32 v[144:145], v[70:71], v[248:249]
	v_pk_fma_f32 v[168:169], v[6:7], v[240:241], v[144:145]
	v_pk_mul_f32 v[146:147], v[8:9], v[250:251]
	v_pk_fma_f32 v[228:229], v[72:73], v[242:243], v[146:147] neg_lo:[0,0,1] neg_hi:[0,0,1]
	v_pk_mul_f32 v[146:147], v[72:73], v[250:251]
	v_pk_fma_f32 v[170:171], v[8:9], v[242:243], v[146:147]
	v_cvt_pk_bf16_f32 v222, v222, v223
	v_cvt_pk_bf16_f32 v223, v224, v225
	v_cvt_pk_bf16_f32 v224, v226, v227
	v_cvt_pk_bf16_f32 v225, v228, v229
	v_cvt_pk_bf16_f32 v164, v164, v165
	v_cvt_pk_bf16_f32 v165, v166, v167
	v_cvt_pk_bf16_f32 v166, v168, v169
	v_cvt_pk_bf16_f32 v167, v170, v171
	v_permlane16_swap_b32_e32 v222, v224
	v_permlane16_swap_b32_e32 v223, v225
	v_permlane16_swap_b32_e32 v164, v166
	v_permlane16_swap_b32_e32 v165, v167
	global_store_dwordx4 v[172:173], v[222:225], off offset:256 sc1
	global_store_dwordx4 v[174:175], v[164:167], off offset:256 sc1
	v_lshrrev_b32_e32 v130, s6, v130
	v_lshl_add_u64 v[172:173], v[172:173], 0, s[28:29]
	v_lshl_add_u64 v[174:175], v[174:175], 0, s[28:29]
	v_and_b32_e32 v130, s7, v130
	v_cvt_f32_i32_e32 v130, v130
	v_mul_f32_e32 v130, s8, v130
	v_add_u32_e32 v131, 129, v148
	v_lshrrev_b32_e32 v131, s6, v131
	v_and_b32_e32 v131, s7, v131
	v_cvt_f32_i32_e32 v131, v131
	v_mul_f32_e32 v131, s8, v131
	v_add_u32_e32 v132, 130, v148
	v_lshrrev_b32_e32 v132, s6, v132
	v_and_b32_e32 v132, s7, v132
	v_cvt_f32_i32_e32 v132, v132
	v_mul_f32_e32 v132, s8, v132
	v_add_u32_e32 v133, 131, v148
	v_lshrrev_b32_e32 v133, s6, v133
	v_and_b32_e32 v133, s7, v133
	v_cvt_f32_i32_e32 v133, v133
	v_mul_f32_e32 v133, s8, v133
	v_add_u32_e32 v134, 144, v148
	v_lshrrev_b32_e32 v134, s6, v134
	v_and_b32_e32 v134, s7, v134
	v_cvt_f32_i32_e32 v134, v134
	v_mul_f32_e32 v134, s8, v134
	v_add_u32_e32 v135, 145, v148
	v_lshrrev_b32_e32 v135, s6, v135
	v_and_b32_e32 v135, s7, v135
	v_cvt_f32_i32_e32 v135, v135
	v_mul_f32_e32 v135, s8, v135
	v_add_u32_e32 v136, 146, v148
	v_lshrrev_b32_e32 v136, s6, v136
	v_and_b32_e32 v136, s7, v136
	v_cvt_f32_i32_e32 v136, v136
	v_mul_f32_e32 v136, s8, v136
	v_add_u32_e32 v137, 147, v148
	v_lshrrev_b32_e32 v137, s6, v137
	v_and_b32_e32 v137, s7, v137
	v_cvt_f32_i32_e32 v137, v137
	v_mul_f32_e32 v137, s8, v137
	v_mov_b32_e32 v142, v160
	v_pk_mul_f32 v[206:207], v[130:131], v[142:143] op_sel_hi:[1,0]
	v_pk_mul_f32 v[208:209], v[132:133], v[142:143] op_sel_hi:[1,0]
	v_pk_mul_f32 v[210:211], v[134:135], v[142:143] op_sel_hi:[1,0]
	v_pk_mul_f32 v[212:213], v[136:137], v[142:143] op_sel_hi:[1,0]
	v_pk_mul_f32 v[206:207], v[206:207], v[138:139]
	v_sin_f32_e32 v214, v206
	v_pk_mul_f32 v[208:209], v[208:209], v[138:139]
	v_sin_f32_e32 v215, v207
	v_pk_mul_f32 v[210:211], v[210:211], v[138:139]
	v_sin_f32_e32 v216, v208
	v_pk_mul_f32 v[212:213], v[212:213], v[138:139]
	v_sin_f32_e32 v217, v209
	v_pk_mul_f32 v[214:215], v[214:215], v[140:141]
	v_sin_f32_e32 v218, v210
	v_pk_mul_f32 v[216:217], v[216:217], v[140:141]
	v_sin_f32_e32 v219, v211
	v_pk_mul_f32 v[144:145], v[58:59], v[214:215]
	v_sin_f32_e32 v220, v212
	v_pk_mul_f32 v[218:219], v[218:219], v[140:141]
	v_sin_f32_e32 v221, v213
	v_pk_mul_f32 v[146:147], v[60:61], v[216:217]
	v_cos_f32_e32 v206, v206
	v_pk_mul_f32 v[220:221], v[220:221], v[140:141]
	v_cos_f32_e32 v207, v207
	v_mov_b32_e32 v142, v161
	v_cos_f32_e32 v208, v208
	v_pk_mul_f32 v[206:207], v[206:207], v[140:141]
	v_cos_f32_e32 v209, v209
	v_pk_fma_f32 v[222:223], v[122:123], v[206:207], v[144:145] neg_lo:[0,0,1] neg_hi:[0,0,1]
	v_cos_f32_e32 v210, v210
	v_pk_mul_f32 v[208:209], v[208:209], v[140:141]
	v_cos_f32_e32 v211, v211
	v_pk_mul_f32 v[144:145], v[122:123], v[214:215]
	v_cos_f32_e32 v212, v212
	v_pk_mul_f32 v[210:211], v[210:211], v[140:141]
	v_cos_f32_e32 v213, v213
	v_pk_fma_f32 v[164:165], v[58:59], v[206:207], v[144:145]
	v_pk_mul_f32 v[212:213], v[212:213], v[140:141]
	v_pk_fma_f32 v[224:225], v[124:125], v[208:209], v[146:147] neg_lo:[0,0,1] neg_hi:[0,0,1]
	v_pk_mul_f32 v[146:147], v[124:125], v[216:217]
	v_pk_fma_f32 v[166:167], v[60:61], v[208:209], v[146:147]
	v_pk_mul_f32 v[144:145], v[50:51], v[218:219]
	v_pk_fma_f32 v[226:227], v[114:115], v[210:211], v[144:145] neg_lo:[0,0,1] neg_hi:[0,0,1]
	v_pk_mul_f32 v[144:145], v[114:115], v[218:219]
	v_pk_fma_f32 v[168:169], v[50:51], v[210:211], v[144:145]
	v_pk_mul_f32 v[146:147], v[52:53], v[220:221]
	v_pk_fma_f32 v[228:229], v[116:117], v[212:213], v[146:147] neg_lo:[0,0,1] neg_hi:[0,0,1]
	v_pk_mul_f32 v[146:147], v[116:117], v[220:221]
	v_pk_fma_f32 v[170:171], v[52:53], v[212:213], v[146:147]
	v_cvt_pk_bf16_f32 v222, v222, v223
	v_cvt_pk_bf16_f32 v223, v224, v225
	v_cvt_pk_bf16_f32 v224, v226, v227
	v_cvt_pk_bf16_f32 v225, v228, v229
	v_cvt_pk_bf16_f32 v164, v164, v165
	v_cvt_pk_bf16_f32 v165, v166, v167
	v_cvt_pk_bf16_f32 v166, v168, v169
	v_cvt_pk_bf16_f32 v167, v170, v171
	v_permlane16_swap_b32_e32 v222, v224
	v_permlane16_swap_b32_e32 v223, v225
	v_permlane16_swap_b32_e32 v164, v166
	v_permlane16_swap_b32_e32 v165, v167
	global_store_dwordx4 v[172:173], v[222:225], off sc1
	global_store_dwordx4 v[174:175], v[164:167], off sc1
	v_pk_mul_f32 v[236:237], v[130:131], v[142:143] op_sel_hi:[1,0]
	v_pk_mul_f32 v[238:239], v[132:133], v[142:143] op_sel_hi:[1,0]
	v_pk_mul_f32 v[240:241], v[134:135], v[142:143] op_sel_hi:[1,0]
	v_pk_mul_f32 v[242:243], v[136:137], v[142:143] op_sel_hi:[1,0]
	v_pk_mul_f32 v[236:237], v[236:237], v[138:139]
	v_sin_f32_e32 v244, v236
	v_pk_mul_f32 v[238:239], v[238:239], v[138:139]
	v_sin_f32_e32 v245, v237
	v_pk_mul_f32 v[240:241], v[240:241], v[138:139]
	v_sin_f32_e32 v246, v238
	v_pk_mul_f32 v[242:243], v[242:243], v[138:139]
	v_sin_f32_e32 v247, v239
	v_pk_mul_f32 v[244:245], v[244:245], v[140:141]
	v_sin_f32_e32 v248, v240
	v_pk_mul_f32 v[246:247], v[246:247], v[140:141]
	v_sin_f32_e32 v249, v241
	v_pk_mul_f32 v[144:145], v[42:43], v[244:245]
	v_sin_f32_e32 v250, v242
	v_pk_mul_f32 v[248:249], v[248:249], v[140:141]
	v_sin_f32_e32 v251, v243
	v_pk_mul_f32 v[146:147], v[44:45], v[246:247]
	v_cos_f32_e32 v236, v236
	v_pk_mul_f32 v[250:251], v[250:251], v[140:141]
	v_cos_f32_e32 v237, v237
	v_mov_b32_e32 v142, v162
	v_cos_f32_e32 v238, v238
	v_pk_mul_f32 v[236:237], v[236:237], v[140:141]
	v_cos_f32_e32 v239, v239
	v_pk_fma_f32 v[222:223], v[106:107], v[236:237], v[144:145] neg_lo:[0,0,1] neg_hi:[0,0,1]
	v_cos_f32_e32 v240, v240
	v_pk_mul_f32 v[238:239], v[238:239], v[140:141]
	v_cos_f32_e32 v241, v241
	v_pk_mul_f32 v[144:145], v[106:107], v[244:245]
	v_cos_f32_e32 v242, v242
	v_pk_mul_f32 v[240:241], v[240:241], v[140:141]
	v_cos_f32_e32 v243, v243
	v_pk_fma_f32 v[164:165], v[42:43], v[236:237], v[144:145]
	v_pk_mul_f32 v[242:243], v[242:243], v[140:141]
	v_pk_fma_f32 v[224:225], v[108:109], v[238:239], v[146:147] neg_lo:[0,0,1] neg_hi:[0,0,1]
	v_pk_mul_f32 v[146:147], v[108:109], v[246:247]
	v_pk_fma_f32 v[166:167], v[44:45], v[238:239], v[146:147]
	v_pk_mul_f32 v[144:145], v[34:35], v[248:249]
	v_pk_fma_f32 v[226:227], v[98:99], v[240:241], v[144:145] neg_lo:[0,0,1] neg_hi:[0,0,1]
	v_pk_mul_f32 v[144:145], v[98:99], v[248:249]
	v_pk_fma_f32 v[168:169], v[34:35], v[240:241], v[144:145]
	v_pk_mul_f32 v[146:147], v[36:37], v[250:251]
	v_pk_fma_f32 v[228:229], v[100:101], v[242:243], v[146:147] neg_lo:[0,0,1] neg_hi:[0,0,1]
	v_pk_mul_f32 v[146:147], v[100:101], v[250:251]
	v_pk_fma_f32 v[170:171], v[36:37], v[242:243], v[146:147]
	v_cvt_pk_bf16_f32 v222, v222, v223
	v_cvt_pk_bf16_f32 v223, v224, v225
	v_cvt_pk_bf16_f32 v224, v226, v227
	v_cvt_pk_bf16_f32 v225, v228, v229
	v_cvt_pk_bf16_f32 v164, v164, v165
	v_cvt_pk_bf16_f32 v165, v166, v167
	v_cvt_pk_bf16_f32 v166, v168, v169
	v_cvt_pk_bf16_f32 v167, v170, v171
	v_permlane16_swap_b32_e32 v222, v224
	v_permlane16_swap_b32_e32 v223, v225
	v_permlane16_swap_b32_e32 v164, v166
	v_permlane16_swap_b32_e32 v165, v167
	global_store_dwordx4 v[172:173], v[222:225], off offset:256 sc1
	global_store_dwordx4 v[174:175], v[164:167], off offset:256 sc1
	v_pk_mul_f32 v[206:207], v[130:131], v[142:143] op_sel_hi:[1,0]
	v_lshl_add_u64 v[172:173], v[172:173], 0, s[2:3]
	v_lshl_add_u64 v[174:175], v[174:175], 0, s[2:3]
	v_pk_mul_f32 v[208:209], v[132:133], v[142:143] op_sel_hi:[1,0]
	v_pk_mul_f32 v[210:211], v[134:135], v[142:143] op_sel_hi:[1,0]
	v_pk_mul_f32 v[212:213], v[136:137], v[142:143] op_sel_hi:[1,0]
	v_pk_mul_f32 v[206:207], v[206:207], v[138:139]
	v_sin_f32_e32 v214, v206
	v_pk_mul_f32 v[208:209], v[208:209], v[138:139]
	v_sin_f32_e32 v215, v207
	v_pk_mul_f32 v[210:211], v[210:211], v[138:139]
	v_sin_f32_e32 v216, v208
	v_pk_mul_f32 v[212:213], v[212:213], v[138:139]
	v_sin_f32_e32 v217, v209
	v_pk_mul_f32 v[214:215], v[214:215], v[140:141]
	v_sin_f32_e32 v218, v210
	v_pk_mul_f32 v[216:217], v[216:217], v[140:141]
	v_sin_f32_e32 v219, v211
	v_pk_mul_f32 v[144:145], v[26:27], v[214:215]
	v_sin_f32_e32 v220, v212
	v_pk_mul_f32 v[218:219], v[218:219], v[140:141]
	v_sin_f32_e32 v221, v213
	v_pk_mul_f32 v[146:147], v[28:29], v[216:217]
	v_cos_f32_e32 v206, v206
	v_pk_mul_f32 v[220:221], v[220:221], v[140:141]
	v_cos_f32_e32 v207, v207
	v_mov_b32_e32 v142, v163
	v_cos_f32_e32 v208, v208
	v_pk_mul_f32 v[206:207], v[206:207], v[140:141]
	v_cos_f32_e32 v209, v209
	v_pk_fma_f32 v[222:223], v[90:91], v[206:207], v[144:145] neg_lo:[0,0,1] neg_hi:[0,0,1]
	v_cos_f32_e32 v210, v210
	v_pk_mul_f32 v[208:209], v[208:209], v[140:141]
	v_cos_f32_e32 v211, v211
	v_pk_mul_f32 v[144:145], v[90:91], v[214:215]
	v_cos_f32_e32 v212, v212
	v_pk_mul_f32 v[210:211], v[210:211], v[140:141]
	v_cos_f32_e32 v213, v213
	v_pk_fma_f32 v[164:165], v[26:27], v[206:207], v[144:145]
	v_pk_mul_f32 v[212:213], v[212:213], v[140:141]
	v_pk_fma_f32 v[224:225], v[92:93], v[208:209], v[146:147] neg_lo:[0,0,1] neg_hi:[0,0,1]
	v_pk_mul_f32 v[146:147], v[92:93], v[216:217]
	v_pk_fma_f32 v[166:167], v[28:29], v[208:209], v[146:147]
	v_pk_mul_f32 v[144:145], v[18:19], v[218:219]
	v_pk_fma_f32 v[226:227], v[82:83], v[210:211], v[144:145] neg_lo:[0,0,1] neg_hi:[0,0,1]
	v_pk_mul_f32 v[144:145], v[82:83], v[218:219]
	v_pk_fma_f32 v[168:169], v[18:19], v[210:211], v[144:145]
	v_pk_mul_f32 v[146:147], v[20:21], v[220:221]
	v_pk_fma_f32 v[228:229], v[84:85], v[212:213], v[146:147] neg_lo:[0,0,1] neg_hi:[0,0,1]
	v_pk_mul_f32 v[146:147], v[84:85], v[220:221]
	v_pk_fma_f32 v[170:171], v[20:21], v[212:213], v[146:147]
	v_cvt_pk_bf16_f32 v222, v222, v223
	v_cvt_pk_bf16_f32 v223, v224, v225
	v_cvt_pk_bf16_f32 v224, v226, v227
	v_cvt_pk_bf16_f32 v225, v228, v229
	v_cvt_pk_bf16_f32 v164, v164, v165
	v_cvt_pk_bf16_f32 v165, v166, v167
	v_cvt_pk_bf16_f32 v166, v168, v169
	v_cvt_pk_bf16_f32 v167, v170, v171
	v_permlane16_swap_b32_e32 v222, v224
	v_permlane16_swap_b32_e32 v223, v225
	v_permlane16_swap_b32_e32 v164, v166
	v_permlane16_swap_b32_e32 v165, v167
	global_store_dwordx4 v[172:173], v[222:225], off sc1
	global_store_dwordx4 v[174:175], v[164:167], off sc1
	v_pk_mul_f32 v[236:237], v[130:131], v[142:143] op_sel_hi:[1,0]
	v_pk_mul_f32 v[238:239], v[132:133], v[142:143] op_sel_hi:[1,0]
	v_pk_mul_f32 v[240:241], v[134:135], v[142:143] op_sel_hi:[1,0]
	v_pk_mul_f32 v[242:243], v[136:137], v[142:143] op_sel_hi:[1,0]
	v_pk_mul_f32 v[236:237], v[236:237], v[138:139]
	v_sin_f32_e32 v244, v236
	v_pk_mul_f32 v[238:239], v[238:239], v[138:139]
	v_sin_f32_e32 v245, v237
	v_pk_mul_f32 v[240:241], v[240:241], v[138:139]
	v_sin_f32_e32 v246, v238
	v_pk_mul_f32 v[242:243], v[242:243], v[138:139]
	v_sin_f32_e32 v247, v239
	v_pk_mul_f32 v[244:245], v[244:245], v[140:141]
	v_sin_f32_e32 v248, v240
	v_pk_mul_f32 v[246:247], v[246:247], v[140:141]
	v_sin_f32_e32 v249, v241
	v_pk_mul_f32 v[144:145], v[10:11], v[244:245]
	v_sin_f32_e32 v250, v242
	v_pk_mul_f32 v[248:249], v[248:249], v[140:141]
	v_sin_f32_e32 v251, v243
	v_pk_mul_f32 v[146:147], v[12:13], v[246:247]
	v_cos_f32_e32 v236, v236
	v_pk_mul_f32 v[250:251], v[250:251], v[140:141]
	v_cos_f32_e32 v237, v237
	v_cos_f32_e32 v238, v238
	v_pk_mul_f32 v[236:237], v[236:237], v[140:141]
	v_cos_f32_e32 v239, v239
	v_pk_fma_f32 v[222:223], v[74:75], v[236:237], v[144:145] neg_lo:[0,0,1] neg_hi:[0,0,1]
	v_cos_f32_e32 v240, v240
	v_pk_mul_f32 v[238:239], v[238:239], v[140:141]
	v_cos_f32_e32 v241, v241
	v_pk_mul_f32 v[144:145], v[74:75], v[244:245]
	v_cos_f32_e32 v242, v242
	v_pk_mul_f32 v[240:241], v[240:241], v[140:141]
	v_cos_f32_e32 v243, v243
	v_pk_fma_f32 v[164:165], v[10:11], v[236:237], v[144:145]
	v_pk_mul_f32 v[242:243], v[242:243], v[140:141]
	v_pk_fma_f32 v[224:225], v[76:77], v[238:239], v[146:147] neg_lo:[0,0,1] neg_hi:[0,0,1]
	v_pk_mul_f32 v[146:147], v[76:77], v[246:247]
	v_pk_fma_f32 v[166:167], v[12:13], v[238:239], v[146:147]
	v_pk_mul_f32 v[144:145], v[2:3], v[248:249]
	v_pk_fma_f32 v[226:227], v[66:67], v[240:241], v[144:145] neg_lo:[0,0,1] neg_hi:[0,0,1]
	v_pk_mul_f32 v[144:145], v[66:67], v[248:249]
	v_pk_fma_f32 v[168:169], v[2:3], v[240:241], v[144:145]
	v_pk_mul_f32 v[146:147], v[4:5], v[250:251]
	v_pk_fma_f32 v[228:229], v[68:69], v[242:243], v[146:147] neg_lo:[0,0,1] neg_hi:[0,0,1]
	v_pk_mul_f32 v[146:147], v[68:69], v[250:251]
	v_pk_fma_f32 v[170:171], v[4:5], v[242:243], v[146:147]
	v_cvt_pk_bf16_f32 v222, v222, v223
	v_cvt_pk_bf16_f32 v223, v224, v225
	v_cvt_pk_bf16_f32 v224, v226, v227
	v_cvt_pk_bf16_f32 v225, v228, v229
	v_cvt_pk_bf16_f32 v164, v164, v165
	v_cvt_pk_bf16_f32 v165, v166, v167
	v_cvt_pk_bf16_f32 v166, v168, v169
	v_cvt_pk_bf16_f32 v167, v170, v171
	v_permlane16_swap_b32_e32 v222, v224
	v_permlane16_swap_b32_e32 v223, v225
	v_permlane16_swap_b32_e32 v164, v166
	v_permlane16_swap_b32_e32 v165, v167
	global_store_dwordx4 v[172:173], v[222:225], off offset:256 sc1
	global_store_dwordx4 v[174:175], v[164:167], off offset:256 sc1
	s_branch .LBB0_816

.Lswiglu_fast:
	s_and_b64 vcc, exec, s[0:1]
	s_cbranch_vccnz .Lswiglu_fast_wt
	s_lshl_b32 s4, s65, 7
	v_subrev_u32_e32 v168, s4, v162
	v_readlane_b32 s4, v253, 35
	v_readlane_b32 s5, v253, 28
	v_mov_b32_e32 v170, s4
	v_mov_b32_e32 v171, s5
	ds_read_b64 v[174:175], v170
	ds_read_b32 v171, v171
	v_lshlrev_b32_e32 v169, 2, v203
	v_sub_u32_e32 v168, v168, v169
	v_and_b32_e32 v169, 1, v203
	v_lshl_add_u32 v168, v169, 4, v168
	v_lshrrev_b32_e32 v169, 1, v203
	v_lshl_add_u32 v168, v169, 3, v168
	v_ashrrev_i32_e32 v169, 31, v168
	v_mov_b32_e32 v176, 0xbfb8aa3b
	v_mov_b32_e32 v177, 0xbfb8aa3b
	s_waitcnt lgkmcnt(0)
	v_readfirstlane_b32 s5, v171
	v_mad_i64_i32 v[172:173], s[2:3], v171, v160, 0
	v_lshl_add_u64 v[174:175], v[168:169], 1, v[174:175]
	v_lshl_add_u64 v[172:173], v[172:173], 1, v[174:175]
	s_lshl_b32 s6, s5, 5
	s_mov_b32 s7, 0
	s_mul_i32 s8, s6, 5
	s_mov_b32 s9, 0
	v_pk_mul_f32 v[206:207], v[126:127], v[176:177]
	v_exp_f32_e32 v206, v206
	v_pk_mul_f32 v[208:209], v[128:129], v[176:177]
	v_exp_f32_e32 v207, v207
	v_pk_mul_f32 v[210:211], v[118:119], v[176:177]
	v_exp_f32_e32 v208, v208
	v_pk_mul_f32 v[212:213], v[120:121], v[176:177]
	v_exp_f32_e32 v209, v209
	v_pk_mul_f32 v[214:215], v[126:127], v[122:123]
	v_exp_f32_e32 v210, v210
	v_pk_mul_f32 v[216:217], v[128:129], v[124:125]
	v_exp_f32_e32 v211, v211
	v_pk_mul_f32 v[218:219], v[118:119], v[114:115]
	v_exp_f32_e32 v212, v212
	v_pk_mul_f32 v[220:221], v[120:121], v[116:117]
	v_exp_f32_e32 v213, v213
	v_pk_add_f32 v[206:207], v[206:207], 1.0 op_sel_hi:[1,0]
	v_rcp_f32_e32 v206, v206
	v_pk_add_f32 v[208:209], v[208:209], 1.0 op_sel_hi:[1,0]
	v_rcp_f32_e32 v207, v207
	v_pk_add_f32 v[210:211], v[210:211], 1.0 op_sel_hi:[1,0]
	v_rcp_f32_e32 v208, v208
	v_pk_add_f32 v[212:213], v[212:213], 1.0 op_sel_hi:[1,0]
	v_rcp_f32_e32 v209, v209
	v_pk_mul_f32 v[214:215], v[214:215], v[206:207]
	v_rcp_f32_e32 v210, v210
	v_pk_mul_f32 v[216:217], v[216:217], v[208:209]
	v_rcp_f32_e32 v211, v211
	v_cvt_pk_bf16_f32 v222, v214, v215
	v_rcp_f32_e32 v212, v212
	v_pk_mul_f32 v[218:219], v[218:219], v[210:211]
	v_rcp_f32_e32 v213, v213
	v_cvt_pk_bf16_f32 v223, v216, v217
	v_pk_mul_f32 v[220:221], v[220:221], v[212:213]
	v_cvt_pk_bf16_f32 v224, v218, v219
	v_cvt_pk_bf16_f32 v225, v220, v221
	v_pk_mul_f32 v[226:227], v[110:111], v[176:177]
	v_exp_f32_e32 v226, v226
	v_permlane16_swap_b32_e32 v222, v224
	v_exp_f32_e32 v227, v227
	v_permlane16_swap_b32_e32 v223, v225
	global_store_dwordx4 v[172:173], v[222:225], off
	v_pk_mul_f32 v[228:229], v[112:113], v[176:177]
	v_exp_f32_e32 v228, v228
	v_lshl_add_u64 v[172:173], v[172:173], 0, s[6:7]
	v_exp_f32_e32 v229, v229
	v_pk_mul_f32 v[236:237], v[102:103], v[176:177]
	v_exp_f32_e32 v236, v236
	v_pk_mul_f32 v[238:239], v[104:105], v[176:177]
	v_exp_f32_e32 v237, v237
	v_pk_mul_f32 v[240:241], v[110:111], v[106:107]
	v_exp_f32_e32 v238, v238
	v_pk_mul_f32 v[242:243], v[112:113], v[108:109]
	v_exp_f32_e32 v239, v239
	v_pk_mul_f32 v[244:245], v[102:103], v[98:99]
	v_pk_mul_f32 v[246:247], v[104:105], v[100:101]
	v_pk_add_f32 v[226:227], v[226:227], 1.0 op_sel_hi:[1,0]
	v_rcp_f32_e32 v226, v226
	v_pk_add_f32 v[228:229], v[228:229], 1.0 op_sel_hi:[1,0]
	v_rcp_f32_e32 v227, v227
	v_pk_add_f32 v[236:237], v[236:237], 1.0 op_sel_hi:[1,0]
	v_rcp_f32_e32 v228, v228
	v_pk_add_f32 v[238:239], v[238:239], 1.0 op_sel_hi:[1,0]
	v_rcp_f32_e32 v229, v229
	v_pk_mul_f32 v[240:241], v[240:241], v[226:227]
	v_rcp_f32_e32 v236, v236
	v_pk_mul_f32 v[242:243], v[242:243], v[228:229]
	v_rcp_f32_e32 v237, v237
	v_cvt_pk_bf16_f32 v164, v240, v241
	v_rcp_f32_e32 v238, v238
	v_pk_mul_f32 v[244:245], v[244:245], v[236:237]
	v_rcp_f32_e32 v239, v239
	v_cvt_pk_bf16_f32 v165, v242, v243
	v_pk_mul_f32 v[246:247], v[246:247], v[238:239]
	v_cvt_pk_bf16_f32 v166, v244, v245
	v_cvt_pk_bf16_f32 v167, v246, v247
	v_pk_mul_f32 v[130:131], v[94:95], v[176:177]
	v_exp_f32_e32 v130, v130
	v_permlane16_swap_b32_e32 v164, v166
	v_exp_f32_e32 v131, v131
	v_permlane16_swap_b32_e32 v165, v167
	global_store_dwordx4 v[172:173], v[164:167], off
	v_pk_mul_f32 v[132:133], v[96:97], v[176:177]
	v_exp_f32_e32 v132, v132
	v_lshl_add_u64 v[172:173], v[172:173], 0, s[6:7]
	v_exp_f32_e32 v133, v133
	v_pk_mul_f32 v[134:135], v[86:87], v[176:177]
	v_exp_f32_e32 v134, v134
	v_pk_mul_f32 v[136:137], v[88:89], v[176:177]
	v_exp_f32_e32 v135, v135
	v_pk_mul_f32 v[138:139], v[94:95], v[90:91]
	v_exp_f32_e32 v136, v136
	v_pk_mul_f32 v[140:141], v[96:97], v[92:93]
	v_exp_f32_e32 v137, v137
	v_pk_mul_f32 v[142:143], v[86:87], v[82:83]
	v_pk_mul_f32 v[144:145], v[88:89], v[84:85]
	v_pk_add_f32 v[130:131], v[130:131], 1.0 op_sel_hi:[1,0]
	v_rcp_f32_e32 v130, v130
	v_pk_add_f32 v[132:133], v[132:133], 1.0 op_sel_hi:[1,0]
	v_rcp_f32_e32 v131, v131
	v_pk_add_f32 v[134:135], v[134:135], 1.0 op_sel_hi:[1,0]
	v_rcp_f32_e32 v132, v132
	v_pk_add_f32 v[136:137], v[136:137], 1.0 op_sel_hi:[1,0]
	v_rcp_f32_e32 v133, v133
	v_pk_mul_f32 v[138:139], v[138:139], v[130:131]
	v_rcp_f32_e32 v134, v134
	v_pk_mul_f32 v[140:141], v[140:141], v[132:133]
	v_rcp_f32_e32 v135, v135
	v_cvt_pk_bf16_f32 v146, v138, v139
	v_rcp_f32_e32 v136, v136
	v_pk_mul_f32 v[142:143], v[142:143], v[134:135]
	v_rcp_f32_e32 v137, v137
	v_cvt_pk_bf16_f32 v147, v140, v141
	v_pk_mul_f32 v[144:145], v[144:145], v[136:137]
	v_cvt_pk_bf16_f32 v148, v142, v143
	v_cvt_pk_bf16_f32 v149, v144, v145
	v_pk_mul_f32 v[206:207], v[78:79], v[176:177]
	v_exp_f32_e32 v206, v206
	v_permlane16_swap_b32_e32 v146, v148
	v_exp_f32_e32 v207, v207
	v_permlane16_swap_b32_e32 v147, v149
	global_store_dwordx4 v[172:173], v[146:149], off
	v_pk_mul_f32 v[208:209], v[80:81], v[176:177]
	v_exp_f32_e32 v208, v208
	v_lshl_add_u64 v[172:173], v[172:173], 0, s[6:7]
	v_exp_f32_e32 v209, v209
	v_pk_mul_f32 v[210:211], v[70:71], v[176:177]
	v_exp_f32_e32 v210, v210
	v_pk_mul_f32 v[212:213], v[72:73], v[176:177]
	v_exp_f32_e32 v211, v211
	v_pk_mul_f32 v[214:215], v[78:79], v[74:75]
	v_exp_f32_e32 v212, v212
	v_pk_mul_f32 v[216:217], v[80:81], v[76:77]
	v_exp_f32_e32 v213, v213
	v_pk_mul_f32 v[218:219], v[70:71], v[66:67]
	v_pk_mul_f32 v[220:221], v[72:73], v[68:69]
	v_pk_add_f32 v[206:207], v[206:207], 1.0 op_sel_hi:[1,0]
	v_rcp_f32_e32 v206, v206
	v_pk_add_f32 v[208:209], v[208:209], 1.0 op_sel_hi:[1,0]
	v_rcp_f32_e32 v207, v207
	v_pk_add_f32 v[210:211], v[210:211], 1.0 op_sel_hi:[1,0]
	v_rcp_f32_e32 v208, v208
	v_pk_add_f32 v[212:213], v[212:213], 1.0 op_sel_hi:[1,0]
	v_rcp_f32_e32 v209, v209
	v_pk_mul_f32 v[214:215], v[214:215], v[206:207]
	v_rcp_f32_e32 v210, v210
	v_pk_mul_f32 v[216:217], v[216:217], v[208:209]
	v_rcp_f32_e32 v211, v211
	v_cvt_pk_bf16_f32 v222, v214, v215
	v_rcp_f32_e32 v212, v212
	v_pk_mul_f32 v[218:219], v[218:219], v[210:211]
	v_rcp_f32_e32 v213, v213
	v_cvt_pk_bf16_f32 v223, v216, v217
	v_pk_mul_f32 v[220:221], v[220:221], v[212:213]
	v_cvt_pk_bf16_f32 v224, v218, v219
	v_cvt_pk_bf16_f32 v225, v220, v221
	v_pk_mul_f32 v[226:227], v[62:63], v[176:177]
	v_exp_f32_e32 v226, v226
	v_permlane16_swap_b32_e32 v222, v224
	v_exp_f32_e32 v227, v227
	v_permlane16_swap_b32_e32 v223, v225
	global_store_dwordx4 v[172:173], v[222:225], off
	v_pk_mul_f32 v[228:229], v[64:65], v[176:177]
	v_exp_f32_e32 v228, v228
	v_lshl_add_u64 v[172:173], v[172:173], 0, s[8:9]
	v_exp_f32_e32 v229, v229
	v_pk_mul_f32 v[236:237], v[54:55], v[176:177]
	v_exp_f32_e32 v236, v236
	v_pk_mul_f32 v[238:239], v[56:57], v[176:177]
	v_exp_f32_e32 v237, v237
	v_pk_mul_f32 v[240:241], v[62:63], v[58:59]
	v_exp_f32_e32 v238, v238
	v_pk_mul_f32 v[242:243], v[64:65], v[60:61]
	v_exp_f32_e32 v239, v239
	v_pk_mul_f32 v[244:245], v[54:55], v[50:51]
	v_pk_mul_f32 v[246:247], v[56:57], v[52:53]
	v_pk_add_f32 v[226:227], v[226:227], 1.0 op_sel_hi:[1,0]
	v_rcp_f32_e32 v226, v226
	v_pk_add_f32 v[228:229], v[228:229], 1.0 op_sel_hi:[1,0]
	v_rcp_f32_e32 v227, v227
	v_pk_add_f32 v[236:237], v[236:237], 1.0 op_sel_hi:[1,0]
	v_rcp_f32_e32 v228, v228
	v_pk_add_f32 v[238:239], v[238:239], 1.0 op_sel_hi:[1,0]
	v_rcp_f32_e32 v229, v229
	v_pk_mul_f32 v[240:241], v[240:241], v[226:227]
	v_rcp_f32_e32 v236, v236
	v_pk_mul_f32 v[242:243], v[242:243], v[228:229]
	v_rcp_f32_e32 v237, v237
	v_cvt_pk_bf16_f32 v164, v240, v241
	v_rcp_f32_e32 v238, v238
	v_pk_mul_f32 v[244:245], v[244:245], v[236:237]
	v_rcp_f32_e32 v239, v239
	v_cvt_pk_bf16_f32 v165, v242, v243
	v_pk_mul_f32 v[246:247], v[246:247], v[238:239]
	v_cvt_pk_bf16_f32 v166, v244, v245
	v_cvt_pk_bf16_f32 v167, v246, v247
	v_pk_mul_f32 v[130:131], v[46:47], v[176:177]
	v_exp_f32_e32 v130, v130
	v_permlane16_swap_b32_e32 v164, v166
	v_exp_f32_e32 v131, v131
	v_permlane16_swap_b32_e32 v165, v167
	global_store_dwordx4 v[172:173], v[164:167], off
	v_pk_mul_f32 v[132:133], v[48:49], v[176:177]
	v_exp_f32_e32 v132, v132
	v_lshl_add_u64 v[172:173], v[172:173], 0, s[6:7]
	v_exp_f32_e32 v133, v133
	v_pk_mul_f32 v[134:135], v[38:39], v[176:177]
	v_exp_f32_e32 v134, v134
	v_pk_mul_f32 v[136:137], v[40:41], v[176:177]
	v_exp_f32_e32 v135, v135
	v_pk_mul_f32 v[138:139], v[46:47], v[42:43]
	v_exp_f32_e32 v136, v136
	v_pk_mul_f32 v[140:141], v[48:49], v[44:45]
	v_exp_f32_e32 v137, v137
	v_pk_mul_f32 v[142:143], v[38:39], v[34:35]
	v_pk_mul_f32 v[144:145], v[40:41], v[36:37]
	v_pk_add_f32 v[130:131], v[130:131], 1.0 op_sel_hi:[1,0]
	v_rcp_f32_e32 v130, v130
	v_pk_add_f32 v[132:133], v[132:133], 1.0 op_sel_hi:[1,0]
	v_rcp_f32_e32 v131, v131
	v_pk_add_f32 v[134:135], v[134:135], 1.0 op_sel_hi:[1,0]
	v_rcp_f32_e32 v132, v132
	v_pk_add_f32 v[136:137], v[136:137], 1.0 op_sel_hi:[1,0]
	v_rcp_f32_e32 v133, v133
	v_pk_mul_f32 v[138:139], v[138:139], v[130:131]
	v_rcp_f32_e32 v134, v134
	v_pk_mul_f32 v[140:141], v[140:141], v[132:133]
	v_rcp_f32_e32 v135, v135
	v_cvt_pk_bf16_f32 v146, v138, v139
	v_rcp_f32_e32 v136, v136
	v_pk_mul_f32 v[142:143], v[142:143], v[134:135]
	v_rcp_f32_e32 v137, v137
	v_cvt_pk_bf16_f32 v147, v140, v141
	v_pk_mul_f32 v[144:145], v[144:145], v[136:137]
	v_cvt_pk_bf16_f32 v148, v142, v143
	v_cvt_pk_bf16_f32 v149, v144, v145
	v_pk_mul_f32 v[206:207], v[30:31], v[176:177]
	v_exp_f32_e32 v206, v206
	v_permlane16_swap_b32_e32 v146, v148
	v_exp_f32_e32 v207, v207
	v_permlane16_swap_b32_e32 v147, v149
	global_store_dwordx4 v[172:173], v[146:149], off
	v_pk_mul_f32 v[208:209], v[32:33], v[176:177]
	v_exp_f32_e32 v208, v208
	v_lshl_add_u64 v[172:173], v[172:173], 0, s[6:7]
	v_exp_f32_e32 v209, v209
	v_pk_mul_f32 v[210:211], v[22:23], v[176:177]
	v_exp_f32_e32 v210, v210
	v_pk_mul_f32 v[212:213], v[24:25], v[176:177]
	v_exp_f32_e32 v211, v211
	v_pk_mul_f32 v[214:215], v[30:31], v[26:27]
	v_exp_f32_e32 v212, v212
	v_pk_mul_f32 v[216:217], v[32:33], v[28:29]
	v_exp_f32_e32 v213, v213
	v_pk_mul_f32 v[218:219], v[22:23], v[18:19]
	v_pk_mul_f32 v[220:221], v[24:25], v[20:21]
	v_pk_add_f32 v[206:207], v[206:207], 1.0 op_sel_hi:[1,0]
	v_rcp_f32_e32 v206, v206
	v_pk_add_f32 v[208:209], v[208:209], 1.0 op_sel_hi:[1,0]
	v_rcp_f32_e32 v207, v207
	v_pk_add_f32 v[210:211], v[210:211], 1.0 op_sel_hi:[1,0]
	v_rcp_f32_e32 v208, v208
	v_pk_add_f32 v[212:213], v[212:213], 1.0 op_sel_hi:[1,0]
	v_rcp_f32_e32 v209, v209
	v_pk_mul_f32 v[214:215], v[214:215], v[206:207]
	v_rcp_f32_e32 v210, v210
	v_pk_mul_f32 v[216:217], v[216:217], v[208:209]
	v_rcp_f32_e32 v211, v211
	v_cvt_pk_bf16_f32 v222, v214, v215
	v_rcp_f32_e32 v212, v212
	v_pk_mul_f32 v[218:219], v[218:219], v[210:211]
	v_rcp_f32_e32 v213, v213
	v_cvt_pk_bf16_f32 v223, v216, v217
	v_pk_mul_f32 v[220:221], v[220:221], v[212:213]
	v_cvt_pk_bf16_f32 v224, v218, v219
	v_cvt_pk_bf16_f32 v225, v220, v221
	v_pk_mul_f32 v[226:227], v[14:15], v[176:177]
	v_exp_f32_e32 v226, v226
	v_permlane16_swap_b32_e32 v222, v224
	v_exp_f32_e32 v227, v227
	v_permlane16_swap_b32_e32 v223, v225
	global_store_dwordx4 v[172:173], v[222:225], off
	v_pk_mul_f32 v[228:229], v[16:17], v[176:177]
	v_exp_f32_e32 v228, v228
	v_lshl_add_u64 v[172:173], v[172:173], 0, s[6:7]
	v_exp_f32_e32 v229, v229
	v_pk_mul_f32 v[236:237], v[6:7], v[176:177]
	v_exp_f32_e32 v236, v236
	v_pk_mul_f32 v[238:239], v[8:9], v[176:177]
	v_exp_f32_e32 v237, v237
	v_pk_mul_f32 v[240:241], v[14:15], v[10:11]
	v_exp_f32_e32 v238, v238
	v_pk_mul_f32 v[242:243], v[16:17], v[12:13]
	v_exp_f32_e32 v239, v239
	v_pk_mul_f32 v[244:245], v[6:7], v[2:3]
	v_pk_mul_f32 v[246:247], v[8:9], v[4:5]
	v_pk_add_f32 v[226:227], v[226:227], 1.0 op_sel_hi:[1,0]
	v_rcp_f32_e32 v226, v226
	v_pk_add_f32 v[228:229], v[228:229], 1.0 op_sel_hi:[1,0]
	v_rcp_f32_e32 v227, v227
	v_pk_add_f32 v[236:237], v[236:237], 1.0 op_sel_hi:[1,0]
	v_rcp_f32_e32 v228, v228
	v_pk_add_f32 v[238:239], v[238:239], 1.0 op_sel_hi:[1,0]
	v_rcp_f32_e32 v229, v229
	v_pk_mul_f32 v[240:241], v[240:241], v[226:227]
	v_rcp_f32_e32 v236, v236
	v_pk_mul_f32 v[242:243], v[242:243], v[228:229]
	v_rcp_f32_e32 v237, v237
	v_cvt_pk_bf16_f32 v164, v240, v241
	v_rcp_f32_e32 v238, v238
	v_pk_mul_f32 v[244:245], v[244:245], v[236:237]
	v_rcp_f32_e32 v239, v239
	v_cvt_pk_bf16_f32 v165, v242, v243
	v_pk_mul_f32 v[246:247], v[246:247], v[238:239]
	v_cvt_pk_bf16_f32 v166, v244, v245
	v_cvt_pk_bf16_f32 v167, v246, v247
	s_nop 0
	v_permlane16_swap_b32_e32 v164, v166
	v_permlane16_swap_b32_e32 v165, v167
	global_store_dwordx4 v[172:173], v[164:167], off
	s_branch .LBB0_816
.Lswiglu_fast_wt:
	s_lshl_b32 s4, s65, 7
	v_subrev_u32_e32 v168, s4, v162
	v_readlane_b32 s4, v253, 35
	v_readlane_b32 s5, v253, 28
	v_mov_b32_e32 v170, s4
	v_mov_b32_e32 v171, s5
	ds_read_b64 v[174:175], v170
	ds_read_b32 v171, v171
	v_lshlrev_b32_e32 v169, 2, v203
	v_sub_u32_e32 v168, v168, v169
	v_and_b32_e32 v169, 1, v203
	v_lshl_add_u32 v168, v169, 4, v168
	v_lshrrev_b32_e32 v169, 1, v203
	v_lshl_add_u32 v168, v169, 3, v168
	v_ashrrev_i32_e32 v169, 31, v168
	v_mov_b32_e32 v176, 0xbfb8aa3b
	v_mov_b32_e32 v177, 0xbfb8aa3b
	s_waitcnt lgkmcnt(0)
	v_readfirstlane_b32 s5, v171
	v_mad_i64_i32 v[172:173], s[2:3], v171, v160, 0
	v_lshl_add_u64 v[174:175], v[168:169], 1, v[174:175]
	v_lshl_add_u64 v[172:173], v[172:173], 1, v[174:175]
	s_lshl_b32 s6, s5, 5
	s_mov_b32 s7, 0
	s_mul_i32 s8, s6, 5
	s_mov_b32 s9, 0
	v_pk_mul_f32 v[206:207], v[126:127], v[176:177]
	v_exp_f32_e32 v206, v206
	v_pk_mul_f32 v[208:209], v[128:129], v[176:177]
	v_exp_f32_e32 v207, v207
	v_pk_mul_f32 v[210:211], v[118:119], v[176:177]
	v_exp_f32_e32 v208, v208
	v_pk_mul_f32 v[212:213], v[120:121], v[176:177]
	v_exp_f32_e32 v209, v209
	v_pk_mul_f32 v[214:215], v[126:127], v[122:123]
	v_exp_f32_e32 v210, v210
	v_pk_mul_f32 v[216:217], v[128:129], v[124:125]
	v_exp_f32_e32 v211, v211
	v_pk_mul_f32 v[218:219], v[118:119], v[114:115]
	v_exp_f32_e32 v212, v212
	v_pk_mul_f32 v[220:221], v[120:121], v[116:117]
	v_exp_f32_e32 v213, v213
	v_pk_add_f32 v[206:207], v[206:207], 1.0 op_sel_hi:[1,0]
	v_rcp_f32_e32 v206, v206
	v_pk_add_f32 v[208:209], v[208:209], 1.0 op_sel_hi:[1,0]
	v_rcp_f32_e32 v207, v207
	v_pk_add_f32 v[210:211], v[210:211], 1.0 op_sel_hi:[1,0]
	v_rcp_f32_e32 v208, v208
	v_pk_add_f32 v[212:213], v[212:213], 1.0 op_sel_hi:[1,0]
	v_rcp_f32_e32 v209, v209
	v_pk_mul_f32 v[214:215], v[214:215], v[206:207]
	v_rcp_f32_e32 v210, v210
	v_pk_mul_f32 v[216:217], v[216:217], v[208:209]
	v_rcp_f32_e32 v211, v211
	v_cvt_pk_bf16_f32 v222, v214, v215
	v_rcp_f32_e32 v212, v212
	v_pk_mul_f32 v[218:219], v[218:219], v[210:211]
	v_rcp_f32_e32 v213, v213
	v_cvt_pk_bf16_f32 v223, v216, v217
	v_pk_mul_f32 v[220:221], v[220:221], v[212:213]
	v_cvt_pk_bf16_f32 v224, v218, v219
	v_cvt_pk_bf16_f32 v225, v220, v221
	v_pk_mul_f32 v[226:227], v[110:111], v[176:177]
	v_exp_f32_e32 v226, v226
	v_permlane16_swap_b32_e32 v222, v224
	v_exp_f32_e32 v227, v227
	v_permlane16_swap_b32_e32 v223, v225
	global_store_dwordx4 v[172:173], v[222:225], off sc1
	v_pk_mul_f32 v[228:229], v[112:113], v[176:177]
	v_exp_f32_e32 v228, v228
	v_lshl_add_u64 v[172:173], v[172:173], 0, s[6:7]
	v_exp_f32_e32 v229, v229
	v_pk_mul_f32 v[236:237], v[102:103], v[176:177]
	v_exp_f32_e32 v236, v236
	v_pk_mul_f32 v[238:239], v[104:105], v[176:177]
	v_exp_f32_e32 v237, v237
	v_pk_mul_f32 v[240:241], v[110:111], v[106:107]
	v_exp_f32_e32 v238, v238
	v_pk_mul_f32 v[242:243], v[112:113], v[108:109]
	v_exp_f32_e32 v239, v239
	v_pk_mul_f32 v[244:245], v[102:103], v[98:99]
	v_pk_mul_f32 v[246:247], v[104:105], v[100:101]
	v_pk_add_f32 v[226:227], v[226:227], 1.0 op_sel_hi:[1,0]
	v_rcp_f32_e32 v226, v226
	v_pk_add_f32 v[228:229], v[228:229], 1.0 op_sel_hi:[1,0]
	v_rcp_f32_e32 v227, v227
	v_pk_add_f32 v[236:237], v[236:237], 1.0 op_sel_hi:[1,0]
	v_rcp_f32_e32 v228, v228
	v_pk_add_f32 v[238:239], v[238:239], 1.0 op_sel_hi:[1,0]
	v_rcp_f32_e32 v229, v229
	v_pk_mul_f32 v[240:241], v[240:241], v[226:227]
	v_rcp_f32_e32 v236, v236
	v_pk_mul_f32 v[242:243], v[242:243], v[228:229]
	v_rcp_f32_e32 v237, v237
	v_cvt_pk_bf16_f32 v164, v240, v241
	v_rcp_f32_e32 v238, v238
	v_pk_mul_f32 v[244:245], v[244:245], v[236:237]
	v_rcp_f32_e32 v239, v239
	v_cvt_pk_bf16_f32 v165, v242, v243
	v_pk_mul_f32 v[246:247], v[246:247], v[238:239]
	v_cvt_pk_bf16_f32 v166, v244, v245
	v_cvt_pk_bf16_f32 v167, v246, v247
	v_pk_mul_f32 v[130:131], v[94:95], v[176:177]
	v_exp_f32_e32 v130, v130
	v_permlane16_swap_b32_e32 v164, v166
	v_exp_f32_e32 v131, v131
	v_permlane16_swap_b32_e32 v165, v167
	global_store_dwordx4 v[172:173], v[164:167], off sc1
	v_pk_mul_f32 v[132:133], v[96:97], v[176:177]
	v_exp_f32_e32 v132, v132
	v_lshl_add_u64 v[172:173], v[172:173], 0, s[6:7]
	v_exp_f32_e32 v133, v133
	v_pk_mul_f32 v[134:135], v[86:87], v[176:177]
	v_exp_f32_e32 v134, v134
	v_pk_mul_f32 v[136:137], v[88:89], v[176:177]
	v_exp_f32_e32 v135, v135
	v_pk_mul_f32 v[138:139], v[94:95], v[90:91]
	v_exp_f32_e32 v136, v136
	v_pk_mul_f32 v[140:141], v[96:97], v[92:93]
	v_exp_f32_e32 v137, v137
	v_pk_mul_f32 v[142:143], v[86:87], v[82:83]
	v_pk_mul_f32 v[144:145], v[88:89], v[84:85]
	v_pk_add_f32 v[130:131], v[130:131], 1.0 op_sel_hi:[1,0]
	v_rcp_f32_e32 v130, v130
	v_pk_add_f32 v[132:133], v[132:133], 1.0 op_sel_hi:[1,0]
	v_rcp_f32_e32 v131, v131
	v_pk_add_f32 v[134:135], v[134:135], 1.0 op_sel_hi:[1,0]
	v_rcp_f32_e32 v132, v132
	v_pk_add_f32 v[136:137], v[136:137], 1.0 op_sel_hi:[1,0]
	v_rcp_f32_e32 v133, v133
	v_pk_mul_f32 v[138:139], v[138:139], v[130:131]
	v_rcp_f32_e32 v134, v134
	v_pk_mul_f32 v[140:141], v[140:141], v[132:133]
	v_rcp_f32_e32 v135, v135
	v_cvt_pk_bf16_f32 v146, v138, v139
	v_rcp_f32_e32 v136, v136
	v_pk_mul_f32 v[142:143], v[142:143], v[134:135]
	v_rcp_f32_e32 v137, v137
	v_cvt_pk_bf16_f32 v147, v140, v141
	v_pk_mul_f32 v[144:145], v[144:145], v[136:137]
	v_cvt_pk_bf16_f32 v148, v142, v143
	v_cvt_pk_bf16_f32 v149, v144, v145
	v_pk_mul_f32 v[206:207], v[78:79], v[176:177]
	v_exp_f32_e32 v206, v206
	v_permlane16_swap_b32_e32 v146, v148
	v_exp_f32_e32 v207, v207
	v_permlane16_swap_b32_e32 v147, v149
	global_store_dwordx4 v[172:173], v[146:149], off sc1
	v_pk_mul_f32 v[208:209], v[80:81], v[176:177]
	v_exp_f32_e32 v208, v208
	v_lshl_add_u64 v[172:173], v[172:173], 0, s[6:7]
	v_exp_f32_e32 v209, v209
	v_pk_mul_f32 v[210:211], v[70:71], v[176:177]
	v_exp_f32_e32 v210, v210
	v_pk_mul_f32 v[212:213], v[72:73], v[176:177]
	v_exp_f32_e32 v211, v211
	v_pk_mul_f32 v[214:215], v[78:79], v[74:75]
	v_exp_f32_e32 v212, v212
	v_pk_mul_f32 v[216:217], v[80:81], v[76:77]
	v_exp_f32_e32 v213, v213
	v_pk_mul_f32 v[218:219], v[70:71], v[66:67]
	v_pk_mul_f32 v[220:221], v[72:73], v[68:69]
	v_pk_add_f32 v[206:207], v[206:207], 1.0 op_sel_hi:[1,0]
	v_rcp_f32_e32 v206, v206
	v_pk_add_f32 v[208:209], v[208:209], 1.0 op_sel_hi:[1,0]
	v_rcp_f32_e32 v207, v207
	v_pk_add_f32 v[210:211], v[210:211], 1.0 op_sel_hi:[1,0]
	v_rcp_f32_e32 v208, v208
	v_pk_add_f32 v[212:213], v[212:213], 1.0 op_sel_hi:[1,0]
	v_rcp_f32_e32 v209, v209
	v_pk_mul_f32 v[214:215], v[214:215], v[206:207]
	v_rcp_f32_e32 v210, v210
	v_pk_mul_f32 v[216:217], v[216:217], v[208:209]
	v_rcp_f32_e32 v211, v211
	v_cvt_pk_bf16_f32 v222, v214, v215
	v_rcp_f32_e32 v212, v212
	v_pk_mul_f32 v[218:219], v[218:219], v[210:211]
	v_rcp_f32_e32 v213, v213
	v_cvt_pk_bf16_f32 v223, v216, v217
	v_pk_mul_f32 v[220:221], v[220:221], v[212:213]
	v_cvt_pk_bf16_f32 v224, v218, v219
	v_cvt_pk_bf16_f32 v225, v220, v221
	v_pk_mul_f32 v[226:227], v[62:63], v[176:177]
	v_exp_f32_e32 v226, v226
	v_permlane16_swap_b32_e32 v222, v224
	v_exp_f32_e32 v227, v227
	v_permlane16_swap_b32_e32 v223, v225
	global_store_dwordx4 v[172:173], v[222:225], off sc1
	v_pk_mul_f32 v[228:229], v[64:65], v[176:177]
	v_exp_f32_e32 v228, v228
	v_lshl_add_u64 v[172:173], v[172:173], 0, s[8:9]
	v_exp_f32_e32 v229, v229
	v_pk_mul_f32 v[236:237], v[54:55], v[176:177]
	v_exp_f32_e32 v236, v236
	v_pk_mul_f32 v[238:239], v[56:57], v[176:177]
	v_exp_f32_e32 v237, v237
	v_pk_mul_f32 v[240:241], v[62:63], v[58:59]
	v_exp_f32_e32 v238, v238
	v_pk_mul_f32 v[242:243], v[64:65], v[60:61]
	v_exp_f32_e32 v239, v239
	v_pk_mul_f32 v[244:245], v[54:55], v[50:51]
	v_pk_mul_f32 v[246:247], v[56:57], v[52:53]
	v_pk_add_f32 v[226:227], v[226:227], 1.0 op_sel_hi:[1,0]
	v_rcp_f32_e32 v226, v226
	v_pk_add_f32 v[228:229], v[228:229], 1.0 op_sel_hi:[1,0]
	v_rcp_f32_e32 v227, v227
	v_pk_add_f32 v[236:237], v[236:237], 1.0 op_sel_hi:[1,0]
	v_rcp_f32_e32 v228, v228
	v_pk_add_f32 v[238:239], v[238:239], 1.0 op_sel_hi:[1,0]
	v_rcp_f32_e32 v229, v229
	v_pk_mul_f32 v[240:241], v[240:241], v[226:227]
	v_rcp_f32_e32 v236, v236
	v_pk_mul_f32 v[242:243], v[242:243], v[228:229]
	v_rcp_f32_e32 v237, v237
	v_cvt_pk_bf16_f32 v164, v240, v241
	v_rcp_f32_e32 v238, v238
	v_pk_mul_f32 v[244:245], v[244:245], v[236:237]
	v_rcp_f32_e32 v239, v239
	v_cvt_pk_bf16_f32 v165, v242, v243
	v_pk_mul_f32 v[246:247], v[246:247], v[238:239]
	v_cvt_pk_bf16_f32 v166, v244, v245
	v_cvt_pk_bf16_f32 v167, v246, v247
	v_pk_mul_f32 v[130:131], v[46:47], v[176:177]
	v_exp_f32_e32 v130, v130
	v_permlane16_swap_b32_e32 v164, v166
	v_exp_f32_e32 v131, v131
	v_permlane16_swap_b32_e32 v165, v167
	global_store_dwordx4 v[172:173], v[164:167], off sc1
	v_pk_mul_f32 v[132:133], v[48:49], v[176:177]
	v_exp_f32_e32 v132, v132
	v_lshl_add_u64 v[172:173], v[172:173], 0, s[6:7]
	v_exp_f32_e32 v133, v133
	v_pk_mul_f32 v[134:135], v[38:39], v[176:177]
	v_exp_f32_e32 v134, v134
	v_pk_mul_f32 v[136:137], v[40:41], v[176:177]
	v_exp_f32_e32 v135, v135
	v_pk_mul_f32 v[138:139], v[46:47], v[42:43]
	v_exp_f32_e32 v136, v136
	v_pk_mul_f32 v[140:141], v[48:49], v[44:45]
	v_exp_f32_e32 v137, v137
	v_pk_mul_f32 v[142:143], v[38:39], v[34:35]
	v_pk_mul_f32 v[144:145], v[40:41], v[36:37]
	v_pk_add_f32 v[130:131], v[130:131], 1.0 op_sel_hi:[1,0]
	v_rcp_f32_e32 v130, v130
	v_pk_add_f32 v[132:133], v[132:133], 1.0 op_sel_hi:[1,0]
	v_rcp_f32_e32 v131, v131
	v_pk_add_f32 v[134:135], v[134:135], 1.0 op_sel_hi:[1,0]
	v_rcp_f32_e32 v132, v132
	v_pk_add_f32 v[136:137], v[136:137], 1.0 op_sel_hi:[1,0]
	v_rcp_f32_e32 v133, v133
	v_pk_mul_f32 v[138:139], v[138:139], v[130:131]
	v_rcp_f32_e32 v134, v134
	v_pk_mul_f32 v[140:141], v[140:141], v[132:133]
	v_rcp_f32_e32 v135, v135
	v_cvt_pk_bf16_f32 v146, v138, v139
	v_rcp_f32_e32 v136, v136
	v_pk_mul_f32 v[142:143], v[142:143], v[134:135]
	v_rcp_f32_e32 v137, v137
	v_cvt_pk_bf16_f32 v147, v140, v141
	v_pk_mul_f32 v[144:145], v[144:145], v[136:137]
	v_cvt_pk_bf16_f32 v148, v142, v143
	v_cvt_pk_bf16_f32 v149, v144, v145
	v_pk_mul_f32 v[206:207], v[30:31], v[176:177]
	v_exp_f32_e32 v206, v206
	v_permlane16_swap_b32_e32 v146, v148
	v_exp_f32_e32 v207, v207
	v_permlane16_swap_b32_e32 v147, v149
	global_store_dwordx4 v[172:173], v[146:149], off sc1
	v_pk_mul_f32 v[208:209], v[32:33], v[176:177]
	v_exp_f32_e32 v208, v208
	v_lshl_add_u64 v[172:173], v[172:173], 0, s[6:7]
	v_exp_f32_e32 v209, v209
	v_pk_mul_f32 v[210:211], v[22:23], v[176:177]
	v_exp_f32_e32 v210, v210
	v_pk_mul_f32 v[212:213], v[24:25], v[176:177]
	v_exp_f32_e32 v211, v211
	v_pk_mul_f32 v[214:215], v[30:31], v[26:27]
	v_exp_f32_e32 v212, v212
	v_pk_mul_f32 v[216:217], v[32:33], v[28:29]
	v_exp_f32_e32 v213, v213
	v_pk_mul_f32 v[218:219], v[22:23], v[18:19]
	v_pk_mul_f32 v[220:221], v[24:25], v[20:21]
	v_pk_add_f32 v[206:207], v[206:207], 1.0 op_sel_hi:[1,0]
	v_rcp_f32_e32 v206, v206
	v_pk_add_f32 v[208:209], v[208:209], 1.0 op_sel_hi:[1,0]
	v_rcp_f32_e32 v207, v207
	v_pk_add_f32 v[210:211], v[210:211], 1.0 op_sel_hi:[1,0]
	v_rcp_f32_e32 v208, v208
	v_pk_add_f32 v[212:213], v[212:213], 1.0 op_sel_hi:[1,0]
	v_rcp_f32_e32 v209, v209
	v_pk_mul_f32 v[214:215], v[214:215], v[206:207]
	v_rcp_f32_e32 v210, v210
	v_pk_mul_f32 v[216:217], v[216:217], v[208:209]
	v_rcp_f32_e32 v211, v211
	v_cvt_pk_bf16_f32 v222, v214, v215
	v_rcp_f32_e32 v212, v212
	v_pk_mul_f32 v[218:219], v[218:219], v[210:211]
	v_rcp_f32_e32 v213, v213
	v_cvt_pk_bf16_f32 v223, v216, v217
	v_pk_mul_f32 v[220:221], v[220:221], v[212:213]
	v_cvt_pk_bf16_f32 v224, v218, v219
	v_cvt_pk_bf16_f32 v225, v220, v221
	v_pk_mul_f32 v[226:227], v[14:15], v[176:177]
	v_exp_f32_e32 v226, v226
	v_permlane16_swap_b32_e32 v222, v224
	v_exp_f32_e32 v227, v227
	v_permlane16_swap_b32_e32 v223, v225
	global_store_dwordx4 v[172:173], v[222:225], off sc1
	v_pk_mul_f32 v[228:229], v[16:17], v[176:177]
	v_exp_f32_e32 v228, v228
	v_lshl_add_u64 v[172:173], v[172:173], 0, s[6:7]
	v_exp_f32_e32 v229, v229
	v_pk_mul_f32 v[236:237], v[6:7], v[176:177]
	v_exp_f32_e32 v236, v236
	v_pk_mul_f32 v[238:239], v[8:9], v[176:177]
	v_exp_f32_e32 v237, v237
	v_pk_mul_f32 v[240:241], v[14:15], v[10:11]
	v_exp_f32_e32 v238, v238
	v_pk_mul_f32 v[242:243], v[16:17], v[12:13]
	v_exp_f32_e32 v239, v239
	v_pk_mul_f32 v[244:245], v[6:7], v[2:3]
	v_pk_mul_f32 v[246:247], v[8:9], v[4:5]
	v_pk_add_f32 v[226:227], v[226:227], 1.0 op_sel_hi:[1,0]
	v_rcp_f32_e32 v226, v226
	v_pk_add_f32 v[228:229], v[228:229], 1.0 op_sel_hi:[1,0]
	v_rcp_f32_e32 v227, v227
	v_pk_add_f32 v[236:237], v[236:237], 1.0 op_sel_hi:[1,0]
	v_rcp_f32_e32 v228, v228
	v_pk_add_f32 v[238:239], v[238:239], 1.0 op_sel_hi:[1,0]
	v_rcp_f32_e32 v229, v229
	v_pk_mul_f32 v[240:241], v[240:241], v[226:227]
	v_rcp_f32_e32 v236, v236
	v_pk_mul_f32 v[242:243], v[242:243], v[228:229]
	v_rcp_f32_e32 v237, v237
	v_cvt_pk_bf16_f32 v164, v240, v241
	v_rcp_f32_e32 v238, v238
	v_pk_mul_f32 v[244:245], v[244:245], v[236:237]
	v_rcp_f32_e32 v239, v239
	v_cvt_pk_bf16_f32 v165, v242, v243
	v_pk_mul_f32 v[246:247], v[246:247], v[238:239]
	v_cvt_pk_bf16_f32 v166, v244, v245
	v_cvt_pk_bf16_f32 v167, v246, v247
	s_nop 0
	v_permlane16_swap_b32_e32 v164, v166
	v_permlane16_swap_b32_e32 v165, v167
	global_store_dwordx4 v[172:173], v[164:167], off sc1
	s_branch .LBB0_816
.Lglu_fast:
	s_and_b64 vcc, exec, s[0:1]
	s_cbranch_vccnz .Lglu_fast_wt
	s_lshl_b32 s4, s65, 7
	v_subrev_u32_e32 v168, s4, v162
	v_readlane_b32 s4, v253, 35
	v_readlane_b32 s5, v253, 28
	v_mov_b32_e32 v170, s4
	v_mov_b32_e32 v171, s5
	ds_read_b64 v[174:175], v170
	ds_read_b32 v171, v171
	v_readlane_b32 s4, v253, 44
	v_mov_b32_e32 v170, s4
	ds_read_b64 v[248:249], v170
	v_ashrrev_i32_e32 v169, 31, v168
	s_mov_b64 s[4:5], 0x1000
	s_waitcnt lgkmcnt(0)
	v_lshl_add_u64 v[248:249], v[168:169], 2, v[248:249]
	global_load_dwordx4 v[130:133], v[248:249], off
	global_load_dwordx4 v[134:137], v[248:249], off offset:64
	v_lshl_add_u64 v[248:249], v[248:249], 0, s[4:5]
	global_load_dwordx4 v[138:141], v[248:249], off
	global_load_dwordx4 v[142:145], v[248:249], off offset:64
	v_lshlrev_b32_e32 v169, 2, v203
	v_sub_u32_e32 v168, v168, v169
	v_and_b32_e32 v169, 1, v203
	v_lshl_add_u32 v168, v169, 4, v168
	v_lshrrev_b32_e32 v169, 1, v203
	v_lshl_add_u32 v168, v169, 3, v168
	v_ashrrev_i32_e32 v169, 31, v168
	v_mov_b32_e32 v176, 0xbfb8aa3b
	v_mov_b32_e32 v177, 0xbfb8aa3b
	s_waitcnt lgkmcnt(0)
	v_readfirstlane_b32 s5, v171
	v_mad_i64_i32 v[172:173], s[2:3], v171, v160, 0
	v_lshl_add_u64 v[174:175], v[168:169], 1, v[174:175]
	v_lshl_add_u64 v[172:173], v[172:173], 1, v[174:175]
	s_lshl_b32 s6, s5, 5
	s_mov_b32 s7, 0
	s_mul_i32 s8, s6, 5
	s_mov_b32 s9, 0
	s_waitcnt vmcnt(0)
	v_pk_add_f32 v[206:207], v[122:123], v[138:139]
	v_pk_add_f32 v[208:209], v[124:125], v[140:141]
	v_pk_add_f32 v[210:211], v[114:115], v[142:143]
	v_pk_add_f32 v[212:213], v[116:117], v[144:145]
	v_pk_mul_f32 v[206:207], v[206:207], v[176:177]
	v_exp_f32_e32 v206, v206
	v_pk_mul_f32 v[208:209], v[208:209], v[176:177]
	v_exp_f32_e32 v207, v207
	v_pk_mul_f32 v[210:211], v[210:211], v[176:177]
	v_exp_f32_e32 v208, v208
	v_pk_mul_f32 v[212:213], v[212:213], v[176:177]
	v_exp_f32_e32 v209, v209
	v_pk_add_f32 v[214:215], v[126:127], v[130:131]
	v_exp_f32_e32 v210, v210
	v_pk_add_f32 v[216:217], v[128:129], v[132:133]
	v_exp_f32_e32 v211, v211
	v_pk_add_f32 v[218:219], v[118:119], v[134:135]
	v_exp_f32_e32 v212, v212
	v_pk_add_f32 v[220:221], v[120:121], v[136:137]
	v_exp_f32_e32 v213, v213
	v_pk_add_f32 v[206:207], v[206:207], 1.0 op_sel_hi:[1,0]
	v_rcp_f32_e32 v206, v206
	v_pk_add_f32 v[208:209], v[208:209], 1.0 op_sel_hi:[1,0]
	v_rcp_f32_e32 v207, v207
	v_pk_add_f32 v[210:211], v[210:211], 1.0 op_sel_hi:[1,0]
	v_rcp_f32_e32 v208, v208
	v_pk_add_f32 v[212:213], v[212:213], 1.0 op_sel_hi:[1,0]
	v_rcp_f32_e32 v209, v209
	v_pk_mul_f32 v[214:215], v[214:215], v[206:207]
	v_rcp_f32_e32 v210, v210
	v_pk_mul_f32 v[216:217], v[216:217], v[208:209]
	v_rcp_f32_e32 v211, v211
	v_cvt_pk_bf16_f32 v222, v214, v215
	v_rcp_f32_e32 v212, v212
	v_pk_mul_f32 v[218:219], v[218:219], v[210:211]
	v_rcp_f32_e32 v213, v213
	v_cvt_pk_bf16_f32 v223, v216, v217
	v_pk_mul_f32 v[220:221], v[220:221], v[212:213]
	v_cvt_pk_bf16_f32 v224, v218, v219
	v_cvt_pk_bf16_f32 v225, v220, v221
	v_pk_add_f32 v[226:227], v[106:107], v[138:139]
	v_permlane16_swap_b32_e32 v222, v224
	v_permlane16_swap_b32_e32 v223, v225
	global_store_dwordx4 v[172:173], v[222:225], off
	v_pk_add_f32 v[228:229], v[108:109], v[140:141]
	v_lshl_add_u64 v[172:173], v[172:173], 0, s[6:7]
	v_pk_add_f32 v[236:237], v[98:99], v[142:143]
	v_pk_add_f32 v[238:239], v[100:101], v[144:145]
	v_pk_mul_f32 v[226:227], v[226:227], v[176:177]
	v_exp_f32_e32 v226, v226
	v_pk_mul_f32 v[228:229], v[228:229], v[176:177]
	v_exp_f32_e32 v227, v227
	v_pk_mul_f32 v[236:237], v[236:237], v[176:177]
	v_exp_f32_e32 v228, v228
	v_pk_mul_f32 v[238:239], v[238:239], v[176:177]
	v_exp_f32_e32 v229, v229
	v_pk_add_f32 v[240:241], v[110:111], v[130:131]
	v_exp_f32_e32 v236, v236
	v_pk_add_f32 v[242:243], v[112:113], v[132:133]
	v_exp_f32_e32 v237, v237
	v_pk_add_f32 v[244:245], v[102:103], v[134:135]
	v_exp_f32_e32 v238, v238
	v_pk_add_f32 v[246:247], v[104:105], v[136:137]
	v_exp_f32_e32 v239, v239
	v_pk_add_f32 v[226:227], v[226:227], 1.0 op_sel_hi:[1,0]
	v_rcp_f32_e32 v226, v226
	v_pk_add_f32 v[228:229], v[228:229], 1.0 op_sel_hi:[1,0]
	v_rcp_f32_e32 v227, v227
	v_pk_add_f32 v[236:237], v[236:237], 1.0 op_sel_hi:[1,0]
	v_rcp_f32_e32 v228, v228
	v_pk_add_f32 v[238:239], v[238:239], 1.0 op_sel_hi:[1,0]
	v_rcp_f32_e32 v229, v229
	v_pk_mul_f32 v[240:241], v[240:241], v[226:227]
	v_rcp_f32_e32 v236, v236
	v_pk_mul_f32 v[242:243], v[242:243], v[228:229]
	v_rcp_f32_e32 v237, v237
	v_cvt_pk_bf16_f32 v164, v240, v241
	v_rcp_f32_e32 v238, v238
	v_pk_mul_f32 v[244:245], v[244:245], v[236:237]
	v_rcp_f32_e32 v239, v239
	v_cvt_pk_bf16_f32 v165, v242, v243
	v_pk_mul_f32 v[246:247], v[246:247], v[238:239]
	v_cvt_pk_bf16_f32 v166, v244, v245
	v_cvt_pk_bf16_f32 v167, v246, v247
	v_pk_add_f32 v[206:207], v[90:91], v[138:139]
	v_permlane16_swap_b32_e32 v164, v166
	v_permlane16_swap_b32_e32 v165, v167
	global_store_dwordx4 v[172:173], v[164:167], off
	v_pk_add_f32 v[208:209], v[92:93], v[140:141]
	v_lshl_add_u64 v[172:173], v[172:173], 0, s[6:7]
	v_pk_add_f32 v[210:211], v[82:83], v[142:143]
	v_pk_add_f32 v[212:213], v[84:85], v[144:145]
	v_pk_mul_f32 v[206:207], v[206:207], v[176:177]
	v_exp_f32_e32 v206, v206
	v_pk_mul_f32 v[208:209], v[208:209], v[176:177]
	v_exp_f32_e32 v207, v207
	v_pk_mul_f32 v[210:211], v[210:211], v[176:177]
	v_exp_f32_e32 v208, v208
	v_pk_mul_f32 v[212:213], v[212:213], v[176:177]
	v_exp_f32_e32 v209, v209
	v_pk_add_f32 v[214:215], v[94:95], v[130:131]
	v_exp_f32_e32 v210, v210
	v_pk_add_f32 v[216:217], v[96:97], v[132:133]
	v_exp_f32_e32 v211, v211
	v_pk_add_f32 v[218:219], v[86:87], v[134:135]
	v_exp_f32_e32 v212, v212
	v_pk_add_f32 v[220:221], v[88:89], v[136:137]
	v_exp_f32_e32 v213, v213
	v_pk_add_f32 v[206:207], v[206:207], 1.0 op_sel_hi:[1,0]
	v_rcp_f32_e32 v206, v206
	v_pk_add_f32 v[208:209], v[208:209], 1.0 op_sel_hi:[1,0]
	v_rcp_f32_e32 v207, v207
	v_pk_add_f32 v[210:211], v[210:211], 1.0 op_sel_hi:[1,0]
	v_rcp_f32_e32 v208, v208
	v_pk_add_f32 v[212:213], v[212:213], 1.0 op_sel_hi:[1,0]
	v_rcp_f32_e32 v209, v209
	v_pk_mul_f32 v[214:215], v[214:215], v[206:207]
	v_rcp_f32_e32 v210, v210
	v_pk_mul_f32 v[216:217], v[216:217], v[208:209]
	v_rcp_f32_e32 v211, v211
	v_cvt_pk_bf16_f32 v222, v214, v215
	v_rcp_f32_e32 v212, v212
	v_pk_mul_f32 v[218:219], v[218:219], v[210:211]
	v_rcp_f32_e32 v213, v213
	v_cvt_pk_bf16_f32 v223, v216, v217
	v_pk_mul_f32 v[220:221], v[220:221], v[212:213]
	v_cvt_pk_bf16_f32 v224, v218, v219
	v_cvt_pk_bf16_f32 v225, v220, v221
	v_pk_add_f32 v[226:227], v[74:75], v[138:139]
	v_permlane16_swap_b32_e32 v222, v224
	v_permlane16_swap_b32_e32 v223, v225
	global_store_dwordx4 v[172:173], v[222:225], off
	v_pk_add_f32 v[228:229], v[76:77], v[140:141]
	v_lshl_add_u64 v[172:173], v[172:173], 0, s[6:7]
	v_pk_add_f32 v[236:237], v[66:67], v[142:143]
	v_pk_add_f32 v[238:239], v[68:69], v[144:145]
	v_pk_mul_f32 v[226:227], v[226:227], v[176:177]
	v_exp_f32_e32 v226, v226
	v_pk_mul_f32 v[228:229], v[228:229], v[176:177]
	v_exp_f32_e32 v227, v227
	v_pk_mul_f32 v[236:237], v[236:237], v[176:177]
	v_exp_f32_e32 v228, v228
	v_pk_mul_f32 v[238:239], v[238:239], v[176:177]
	v_exp_f32_e32 v229, v229
	v_pk_add_f32 v[240:241], v[78:79], v[130:131]
	v_exp_f32_e32 v236, v236
	v_pk_add_f32 v[242:243], v[80:81], v[132:133]
	v_exp_f32_e32 v237, v237
	v_pk_add_f32 v[244:245], v[70:71], v[134:135]
	v_exp_f32_e32 v238, v238
	v_pk_add_f32 v[246:247], v[72:73], v[136:137]
	v_exp_f32_e32 v239, v239
	v_pk_add_f32 v[226:227], v[226:227], 1.0 op_sel_hi:[1,0]
	v_rcp_f32_e32 v226, v226
	v_pk_add_f32 v[228:229], v[228:229], 1.0 op_sel_hi:[1,0]
	v_rcp_f32_e32 v227, v227
	v_pk_add_f32 v[236:237], v[236:237], 1.0 op_sel_hi:[1,0]
	v_rcp_f32_e32 v228, v228
	v_pk_add_f32 v[238:239], v[238:239], 1.0 op_sel_hi:[1,0]
	v_rcp_f32_e32 v229, v229
	v_pk_mul_f32 v[240:241], v[240:241], v[226:227]
	v_rcp_f32_e32 v236, v236
	v_pk_mul_f32 v[242:243], v[242:243], v[228:229]
	v_rcp_f32_e32 v237, v237
	v_cvt_pk_bf16_f32 v164, v240, v241
	v_rcp_f32_e32 v238, v238
	v_pk_mul_f32 v[244:245], v[244:245], v[236:237]
	v_rcp_f32_e32 v239, v239
	v_cvt_pk_bf16_f32 v165, v242, v243
	v_pk_mul_f32 v[246:247], v[246:247], v[238:239]
	v_cvt_pk_bf16_f32 v166, v244, v245
	v_cvt_pk_bf16_f32 v167, v246, v247
	v_pk_add_f32 v[206:207], v[58:59], v[138:139]
	v_permlane16_swap_b32_e32 v164, v166
	v_permlane16_swap_b32_e32 v165, v167
	global_store_dwordx4 v[172:173], v[164:167], off
	v_pk_add_f32 v[208:209], v[60:61], v[140:141]
	v_lshl_add_u64 v[172:173], v[172:173], 0, s[8:9]
	v_pk_add_f32 v[210:211], v[50:51], v[142:143]
	v_pk_add_f32 v[212:213], v[52:53], v[144:145]
	v_pk_mul_f32 v[206:207], v[206:207], v[176:177]
	v_exp_f32_e32 v206, v206
	v_pk_mul_f32 v[208:209], v[208:209], v[176:177]
	v_exp_f32_e32 v207, v207
	v_pk_mul_f32 v[210:211], v[210:211], v[176:177]
	v_exp_f32_e32 v208, v208
	v_pk_mul_f32 v[212:213], v[212:213], v[176:177]
	v_exp_f32_e32 v209, v209
	v_pk_add_f32 v[214:215], v[62:63], v[130:131]
	v_exp_f32_e32 v210, v210
	v_pk_add_f32 v[216:217], v[64:65], v[132:133]
	v_exp_f32_e32 v211, v211
	v_pk_add_f32 v[218:219], v[54:55], v[134:135]
	v_exp_f32_e32 v212, v212
	v_pk_add_f32 v[220:221], v[56:57], v[136:137]
	v_exp_f32_e32 v213, v213
	v_pk_add_f32 v[206:207], v[206:207], 1.0 op_sel_hi:[1,0]
	v_rcp_f32_e32 v206, v206
	v_pk_add_f32 v[208:209], v[208:209], 1.0 op_sel_hi:[1,0]
	v_rcp_f32_e32 v207, v207
	v_pk_add_f32 v[210:211], v[210:211], 1.0 op_sel_hi:[1,0]
	v_rcp_f32_e32 v208, v208
	v_pk_add_f32 v[212:213], v[212:213], 1.0 op_sel_hi:[1,0]
	v_rcp_f32_e32 v209, v209
	v_pk_mul_f32 v[214:215], v[214:215], v[206:207]
	v_rcp_f32_e32 v210, v210
	v_pk_mul_f32 v[216:217], v[216:217], v[208:209]
	v_rcp_f32_e32 v211, v211
	v_cvt_pk_bf16_f32 v222, v214, v215
	v_rcp_f32_e32 v212, v212
	v_pk_mul_f32 v[218:219], v[218:219], v[210:211]
	v_rcp_f32_e32 v213, v213
	v_cvt_pk_bf16_f32 v223, v216, v217
	v_pk_mul_f32 v[220:221], v[220:221], v[212:213]
	v_cvt_pk_bf16_f32 v224, v218, v219
	v_cvt_pk_bf16_f32 v225, v220, v221
	v_pk_add_f32 v[226:227], v[42:43], v[138:139]
	v_permlane16_swap_b32_e32 v222, v224
	v_permlane16_swap_b32_e32 v223, v225
	global_store_dwordx4 v[172:173], v[222:225], off
	v_pk_add_f32 v[228:229], v[44:45], v[140:141]
	v_lshl_add_u64 v[172:173], v[172:173], 0, s[6:7]
	v_pk_add_f32 v[236:237], v[34:35], v[142:143]
	v_pk_add_f32 v[238:239], v[36:37], v[144:145]
	v_pk_mul_f32 v[226:227], v[226:227], v[176:177]
	v_exp_f32_e32 v226, v226
	v_pk_mul_f32 v[228:229], v[228:229], v[176:177]
	v_exp_f32_e32 v227, v227
	v_pk_mul_f32 v[236:237], v[236:237], v[176:177]
	v_exp_f32_e32 v228, v228
	v_pk_mul_f32 v[238:239], v[238:239], v[176:177]
	v_exp_f32_e32 v229, v229
	v_pk_add_f32 v[240:241], v[46:47], v[130:131]
	v_exp_f32_e32 v236, v236
	v_pk_add_f32 v[242:243], v[48:49], v[132:133]
	v_exp_f32_e32 v237, v237
	v_pk_add_f32 v[244:245], v[38:39], v[134:135]
	v_exp_f32_e32 v238, v238
	v_pk_add_f32 v[246:247], v[40:41], v[136:137]
	v_exp_f32_e32 v239, v239
	v_pk_add_f32 v[226:227], v[226:227], 1.0 op_sel_hi:[1,0]
	v_rcp_f32_e32 v226, v226
	v_pk_add_f32 v[228:229], v[228:229], 1.0 op_sel_hi:[1,0]
	v_rcp_f32_e32 v227, v227
	v_pk_add_f32 v[236:237], v[236:237], 1.0 op_sel_hi:[1,0]
	v_rcp_f32_e32 v228, v228
	v_pk_add_f32 v[238:239], v[238:239], 1.0 op_sel_hi:[1,0]
	v_rcp_f32_e32 v229, v229
	v_pk_mul_f32 v[240:241], v[240:241], v[226:227]
	v_rcp_f32_e32 v236, v236
	v_pk_mul_f32 v[242:243], v[242:243], v[228:229]
	v_rcp_f32_e32 v237, v237
	v_cvt_pk_bf16_f32 v164, v240, v241
	v_rcp_f32_e32 v238, v238
	v_pk_mul_f32 v[244:245], v[244:245], v[236:237]
	v_rcp_f32_e32 v239, v239
	v_cvt_pk_bf16_f32 v165, v242, v243
	v_pk_mul_f32 v[246:247], v[246:247], v[238:239]
	v_cvt_pk_bf16_f32 v166, v244, v245
	v_cvt_pk_bf16_f32 v167, v246, v247
	v_pk_add_f32 v[206:207], v[26:27], v[138:139]
	v_permlane16_swap_b32_e32 v164, v166
	v_permlane16_swap_b32_e32 v165, v167
	global_store_dwordx4 v[172:173], v[164:167], off
	v_pk_add_f32 v[208:209], v[28:29], v[140:141]
	v_lshl_add_u64 v[172:173], v[172:173], 0, s[6:7]
	v_pk_add_f32 v[210:211], v[18:19], v[142:143]
	v_pk_add_f32 v[212:213], v[20:21], v[144:145]
	v_pk_mul_f32 v[206:207], v[206:207], v[176:177]
	v_exp_f32_e32 v206, v206
	v_pk_mul_f32 v[208:209], v[208:209], v[176:177]
	v_exp_f32_e32 v207, v207
	v_pk_mul_f32 v[210:211], v[210:211], v[176:177]
	v_exp_f32_e32 v208, v208
	v_pk_mul_f32 v[212:213], v[212:213], v[176:177]
	v_exp_f32_e32 v209, v209
	v_pk_add_f32 v[214:215], v[30:31], v[130:131]
	v_exp_f32_e32 v210, v210
	v_pk_add_f32 v[216:217], v[32:33], v[132:133]
	v_exp_f32_e32 v211, v211
	v_pk_add_f32 v[218:219], v[22:23], v[134:135]
	v_exp_f32_e32 v212, v212
	v_pk_add_f32 v[220:221], v[24:25], v[136:137]
	v_exp_f32_e32 v213, v213
	v_pk_add_f32 v[206:207], v[206:207], 1.0 op_sel_hi:[1,0]
	v_rcp_f32_e32 v206, v206
	v_pk_add_f32 v[208:209], v[208:209], 1.0 op_sel_hi:[1,0]
	v_rcp_f32_e32 v207, v207
	v_pk_add_f32 v[210:211], v[210:211], 1.0 op_sel_hi:[1,0]
	v_rcp_f32_e32 v208, v208
	v_pk_add_f32 v[212:213], v[212:213], 1.0 op_sel_hi:[1,0]
	v_rcp_f32_e32 v209, v209
	v_pk_mul_f32 v[214:215], v[214:215], v[206:207]
	v_rcp_f32_e32 v210, v210
	v_pk_mul_f32 v[216:217], v[216:217], v[208:209]
	v_rcp_f32_e32 v211, v211
	v_cvt_pk_bf16_f32 v222, v214, v215
	v_rcp_f32_e32 v212, v212
	v_pk_mul_f32 v[218:219], v[218:219], v[210:211]
	v_rcp_f32_e32 v213, v213
	v_cvt_pk_bf16_f32 v223, v216, v217
	v_pk_mul_f32 v[220:221], v[220:221], v[212:213]
	v_cvt_pk_bf16_f32 v224, v218, v219
	v_cvt_pk_bf16_f32 v225, v220, v221
	v_pk_add_f32 v[226:227], v[10:11], v[138:139]
	v_permlane16_swap_b32_e32 v222, v224
	v_permlane16_swap_b32_e32 v223, v225
	global_store_dwordx4 v[172:173], v[222:225], off
	v_pk_add_f32 v[228:229], v[12:13], v[140:141]
	v_lshl_add_u64 v[172:173], v[172:173], 0, s[6:7]
	v_pk_add_f32 v[236:237], v[2:3], v[142:143]
	v_pk_add_f32 v[238:239], v[4:5], v[144:145]
	v_pk_mul_f32 v[226:227], v[226:227], v[176:177]
	v_exp_f32_e32 v226, v226
	v_pk_mul_f32 v[228:229], v[228:229], v[176:177]
	v_exp_f32_e32 v227, v227
	v_pk_mul_f32 v[236:237], v[236:237], v[176:177]
	v_exp_f32_e32 v228, v228
	v_pk_mul_f32 v[238:239], v[238:239], v[176:177]
	v_exp_f32_e32 v229, v229
	v_pk_add_f32 v[240:241], v[14:15], v[130:131]
	v_exp_f32_e32 v236, v236
	v_pk_add_f32 v[242:243], v[16:17], v[132:133]
	v_exp_f32_e32 v237, v237
	v_pk_add_f32 v[244:245], v[6:7], v[134:135]
	v_exp_f32_e32 v238, v238
	v_pk_add_f32 v[246:247], v[8:9], v[136:137]
	v_exp_f32_e32 v239, v239
	v_pk_add_f32 v[226:227], v[226:227], 1.0 op_sel_hi:[1,0]
	v_rcp_f32_e32 v226, v226
	v_pk_add_f32 v[228:229], v[228:229], 1.0 op_sel_hi:[1,0]
	v_rcp_f32_e32 v227, v227
	v_pk_add_f32 v[236:237], v[236:237], 1.0 op_sel_hi:[1,0]
	v_rcp_f32_e32 v228, v228
	v_pk_add_f32 v[238:239], v[238:239], 1.0 op_sel_hi:[1,0]
	v_rcp_f32_e32 v229, v229
	v_pk_mul_f32 v[240:241], v[240:241], v[226:227]
	v_rcp_f32_e32 v236, v236
	v_pk_mul_f32 v[242:243], v[242:243], v[228:229]
	v_rcp_f32_e32 v237, v237
	v_cvt_pk_bf16_f32 v164, v240, v241
	v_rcp_f32_e32 v238, v238
	v_pk_mul_f32 v[244:245], v[244:245], v[236:237]
	v_rcp_f32_e32 v239, v239
	v_cvt_pk_bf16_f32 v165, v242, v243
	v_pk_mul_f32 v[246:247], v[246:247], v[238:239]
	v_cvt_pk_bf16_f32 v166, v244, v245
	v_cvt_pk_bf16_f32 v167, v246, v247
	s_nop 0
	v_permlane16_swap_b32_e32 v164, v166
	v_permlane16_swap_b32_e32 v165, v167
	global_store_dwordx4 v[172:173], v[164:167], off
	s_branch .LBB0_816
.Lglu_fast_wt:
	s_lshl_b32 s4, s65, 7
	v_subrev_u32_e32 v168, s4, v162
	v_readlane_b32 s4, v253, 35
	v_readlane_b32 s5, v253, 28
	v_mov_b32_e32 v170, s4
	v_mov_b32_e32 v171, s5
	ds_read_b64 v[174:175], v170
	ds_read_b32 v171, v171
	v_readlane_b32 s4, v253, 44
	v_mov_b32_e32 v170, s4
	ds_read_b64 v[248:249], v170
	v_ashrrev_i32_e32 v169, 31, v168
	s_mov_b64 s[4:5], 0x1000
	s_waitcnt lgkmcnt(0)
	v_lshl_add_u64 v[248:249], v[168:169], 2, v[248:249]
	global_load_dwordx4 v[130:133], v[248:249], off
	global_load_dwordx4 v[134:137], v[248:249], off offset:64
	v_lshl_add_u64 v[248:249], v[248:249], 0, s[4:5]
	global_load_dwordx4 v[138:141], v[248:249], off
	global_load_dwordx4 v[142:145], v[248:249], off offset:64
	v_lshlrev_b32_e32 v169, 2, v203
	v_sub_u32_e32 v168, v168, v169
	v_and_b32_e32 v169, 1, v203
	v_lshl_add_u32 v168, v169, 4, v168
	v_lshrrev_b32_e32 v169, 1, v203
	v_lshl_add_u32 v168, v169, 3, v168
	v_ashrrev_i32_e32 v169, 31, v168
	v_mov_b32_e32 v176, 0xbfb8aa3b
	v_mov_b32_e32 v177, 0xbfb8aa3b
	s_waitcnt lgkmcnt(0)
	v_readfirstlane_b32 s5, v171
	v_mad_i64_i32 v[172:173], s[2:3], v171, v160, 0
	v_lshl_add_u64 v[174:175], v[168:169], 1, v[174:175]
	v_lshl_add_u64 v[172:173], v[172:173], 1, v[174:175]
	s_lshl_b32 s6, s5, 5
	s_mov_b32 s7, 0
	s_mul_i32 s8, s6, 5
	s_mov_b32 s9, 0
	s_waitcnt vmcnt(0)
	v_pk_add_f32 v[206:207], v[122:123], v[138:139]
	v_pk_add_f32 v[208:209], v[124:125], v[140:141]
	v_pk_add_f32 v[210:211], v[114:115], v[142:143]
	v_pk_add_f32 v[212:213], v[116:117], v[144:145]
	v_pk_mul_f32 v[206:207], v[206:207], v[176:177]
	v_exp_f32_e32 v206, v206
	v_pk_mul_f32 v[208:209], v[208:209], v[176:177]
	v_exp_f32_e32 v207, v207
	v_pk_mul_f32 v[210:211], v[210:211], v[176:177]
	v_exp_f32_e32 v208, v208
	v_pk_mul_f32 v[212:213], v[212:213], v[176:177]
	v_exp_f32_e32 v209, v209
	v_pk_add_f32 v[214:215], v[126:127], v[130:131]
	v_exp_f32_e32 v210, v210
	v_pk_add_f32 v[216:217], v[128:129], v[132:133]
	v_exp_f32_e32 v211, v211
	v_pk_add_f32 v[218:219], v[118:119], v[134:135]
	v_exp_f32_e32 v212, v212
	v_pk_add_f32 v[220:221], v[120:121], v[136:137]
	v_exp_f32_e32 v213, v213
	v_pk_add_f32 v[206:207], v[206:207], 1.0 op_sel_hi:[1,0]
	v_rcp_f32_e32 v206, v206
	v_pk_add_f32 v[208:209], v[208:209], 1.0 op_sel_hi:[1,0]
	v_rcp_f32_e32 v207, v207
	v_pk_add_f32 v[210:211], v[210:211], 1.0 op_sel_hi:[1,0]
	v_rcp_f32_e32 v208, v208
	v_pk_add_f32 v[212:213], v[212:213], 1.0 op_sel_hi:[1,0]
	v_rcp_f32_e32 v209, v209
	v_pk_mul_f32 v[214:215], v[214:215], v[206:207]
	v_rcp_f32_e32 v210, v210
	v_pk_mul_f32 v[216:217], v[216:217], v[208:209]
	v_rcp_f32_e32 v211, v211
	v_cvt_pk_bf16_f32 v222, v214, v215
	v_rcp_f32_e32 v212, v212
	v_pk_mul_f32 v[218:219], v[218:219], v[210:211]
	v_rcp_f32_e32 v213, v213
	v_cvt_pk_bf16_f32 v223, v216, v217
	v_pk_mul_f32 v[220:221], v[220:221], v[212:213]
	v_cvt_pk_bf16_f32 v224, v218, v219
	v_cvt_pk_bf16_f32 v225, v220, v221
	v_pk_add_f32 v[226:227], v[106:107], v[138:139]
	v_permlane16_swap_b32_e32 v222, v224
	v_permlane16_swap_b32_e32 v223, v225
	global_store_dwordx4 v[172:173], v[222:225], off sc1
	v_pk_add_f32 v[228:229], v[108:109], v[140:141]
	v_lshl_add_u64 v[172:173], v[172:173], 0, s[6:7]
	v_pk_add_f32 v[236:237], v[98:99], v[142:143]
	v_pk_add_f32 v[238:239], v[100:101], v[144:145]
	v_pk_mul_f32 v[226:227], v[226:227], v[176:177]
	v_exp_f32_e32 v226, v226
	v_pk_mul_f32 v[228:229], v[228:229], v[176:177]
	v_exp_f32_e32 v227, v227
	v_pk_mul_f32 v[236:237], v[236:237], v[176:177]
	v_exp_f32_e32 v228, v228
	v_pk_mul_f32 v[238:239], v[238:239], v[176:177]
	v_exp_f32_e32 v229, v229
	v_pk_add_f32 v[240:241], v[110:111], v[130:131]
	v_exp_f32_e32 v236, v236
	v_pk_add_f32 v[242:243], v[112:113], v[132:133]
	v_exp_f32_e32 v237, v237
	v_pk_add_f32 v[244:245], v[102:103], v[134:135]
	v_exp_f32_e32 v238, v238
	v_pk_add_f32 v[246:247], v[104:105], v[136:137]
	v_exp_f32_e32 v239, v239
	v_pk_add_f32 v[226:227], v[226:227], 1.0 op_sel_hi:[1,0]
	v_rcp_f32_e32 v226, v226
	v_pk_add_f32 v[228:229], v[228:229], 1.0 op_sel_hi:[1,0]
	v_rcp_f32_e32 v227, v227
	v_pk_add_f32 v[236:237], v[236:237], 1.0 op_sel_hi:[1,0]
	v_rcp_f32_e32 v228, v228
	v_pk_add_f32 v[238:239], v[238:239], 1.0 op_sel_hi:[1,0]
	v_rcp_f32_e32 v229, v229
	v_pk_mul_f32 v[240:241], v[240:241], v[226:227]
	v_rcp_f32_e32 v236, v236
	v_pk_mul_f32 v[242:243], v[242:243], v[228:229]
	v_rcp_f32_e32 v237, v237
	v_cvt_pk_bf16_f32 v164, v240, v241
	v_rcp_f32_e32 v238, v238
	v_pk_mul_f32 v[244:245], v[244:245], v[236:237]
	v_rcp_f32_e32 v239, v239
	v_cvt_pk_bf16_f32 v165, v242, v243
	v_pk_mul_f32 v[246:247], v[246:247], v[238:239]
	v_cvt_pk_bf16_f32 v166, v244, v245
	v_cvt_pk_bf16_f32 v167, v246, v247
	v_pk_add_f32 v[206:207], v[90:91], v[138:139]
	v_permlane16_swap_b32_e32 v164, v166
	v_permlane16_swap_b32_e32 v165, v167
	global_store_dwordx4 v[172:173], v[164:167], off sc1
	v_pk_add_f32 v[208:209], v[92:93], v[140:141]
	v_lshl_add_u64 v[172:173], v[172:173], 0, s[6:7]
	v_pk_add_f32 v[210:211], v[82:83], v[142:143]
	v_pk_add_f32 v[212:213], v[84:85], v[144:145]
	v_pk_mul_f32 v[206:207], v[206:207], v[176:177]
	v_exp_f32_e32 v206, v206
	v_pk_mul_f32 v[208:209], v[208:209], v[176:177]
	v_exp_f32_e32 v207, v207
	v_pk_mul_f32 v[210:211], v[210:211], v[176:177]
	v_exp_f32_e32 v208, v208
	v_pk_mul_f32 v[212:213], v[212:213], v[176:177]
	v_exp_f32_e32 v209, v209
	v_pk_add_f32 v[214:215], v[94:95], v[130:131]
	v_exp_f32_e32 v210, v210
	v_pk_add_f32 v[216:217], v[96:97], v[132:133]
	v_exp_f32_e32 v211, v211
	v_pk_add_f32 v[218:219], v[86:87], v[134:135]
	v_exp_f32_e32 v212, v212
	v_pk_add_f32 v[220:221], v[88:89], v[136:137]
	v_exp_f32_e32 v213, v213
	v_pk_add_f32 v[206:207], v[206:207], 1.0 op_sel_hi:[1,0]
	v_rcp_f32_e32 v206, v206
	v_pk_add_f32 v[208:209], v[208:209], 1.0 op_sel_hi:[1,0]
	v_rcp_f32_e32 v207, v207
	v_pk_add_f32 v[210:211], v[210:211], 1.0 op_sel_hi:[1,0]
	v_rcp_f32_e32 v208, v208
	v_pk_add_f32 v[212:213], v[212:213], 1.0 op_sel_hi:[1,0]
	v_rcp_f32_e32 v209, v209
	v_pk_mul_f32 v[214:215], v[214:215], v[206:207]
	v_rcp_f32_e32 v210, v210
	v_pk_mul_f32 v[216:217], v[216:217], v[208:209]
	v_rcp_f32_e32 v211, v211
	v_cvt_pk_bf16_f32 v222, v214, v215
	v_rcp_f32_e32 v212, v212
	v_pk_mul_f32 v[218:219], v[218:219], v[210:211]
	v_rcp_f32_e32 v213, v213
	v_cvt_pk_bf16_f32 v223, v216, v217
	v_pk_mul_f32 v[220:221], v[220:221], v[212:213]
	v_cvt_pk_bf16_f32 v224, v218, v219
	v_cvt_pk_bf16_f32 v225, v220, v221
	v_pk_add_f32 v[226:227], v[74:75], v[138:139]
	v_permlane16_swap_b32_e32 v222, v224
	v_permlane16_swap_b32_e32 v223, v225
	global_store_dwordx4 v[172:173], v[222:225], off sc1
	v_pk_add_f32 v[228:229], v[76:77], v[140:141]
	v_lshl_add_u64 v[172:173], v[172:173], 0, s[6:7]
	v_pk_add_f32 v[236:237], v[66:67], v[142:143]
	v_pk_add_f32 v[238:239], v[68:69], v[144:145]
	v_pk_mul_f32 v[226:227], v[226:227], v[176:177]
	v_exp_f32_e32 v226, v226
	v_pk_mul_f32 v[228:229], v[228:229], v[176:177]
	v_exp_f32_e32 v227, v227
	v_pk_mul_f32 v[236:237], v[236:237], v[176:177]
	v_exp_f32_e32 v228, v228
	v_pk_mul_f32 v[238:239], v[238:239], v[176:177]
	v_exp_f32_e32 v229, v229
	v_pk_add_f32 v[240:241], v[78:79], v[130:131]
	v_exp_f32_e32 v236, v236
	v_pk_add_f32 v[242:243], v[80:81], v[132:133]
	v_exp_f32_e32 v237, v237
	v_pk_add_f32 v[244:245], v[70:71], v[134:135]
	v_exp_f32_e32 v238, v238
	v_pk_add_f32 v[246:247], v[72:73], v[136:137]
	v_exp_f32_e32 v239, v239
	v_pk_add_f32 v[226:227], v[226:227], 1.0 op_sel_hi:[1,0]
	v_rcp_f32_e32 v226, v226
	v_pk_add_f32 v[228:229], v[228:229], 1.0 op_sel_hi:[1,0]
	v_rcp_f32_e32 v227, v227
	v_pk_add_f32 v[236:237], v[236:237], 1.0 op_sel_hi:[1,0]
	v_rcp_f32_e32 v228, v228
	v_pk_add_f32 v[238:239], v[238:239], 1.0 op_sel_hi:[1,0]
	v_rcp_f32_e32 v229, v229
	v_pk_mul_f32 v[240:241], v[240:241], v[226:227]
	v_rcp_f32_e32 v236, v236
	v_pk_mul_f32 v[242:243], v[242:243], v[228:229]
	v_rcp_f32_e32 v237, v237
	v_cvt_pk_bf16_f32 v164, v240, v241
	v_rcp_f32_e32 v238, v238
	v_pk_mul_f32 v[244:245], v[244:245], v[236:237]
	v_rcp_f32_e32 v239, v239
	v_cvt_pk_bf16_f32 v165, v242, v243
	v_pk_mul_f32 v[246:247], v[246:247], v[238:239]
	v_cvt_pk_bf16_f32 v166, v244, v245
	v_cvt_pk_bf16_f32 v167, v246, v247
	v_pk_add_f32 v[206:207], v[58:59], v[138:139]
	v_permlane16_swap_b32_e32 v164, v166
	v_permlane16_swap_b32_e32 v165, v167
	global_store_dwordx4 v[172:173], v[164:167], off sc1
	v_pk_add_f32 v[208:209], v[60:61], v[140:141]
	v_lshl_add_u64 v[172:173], v[172:173], 0, s[8:9]
	v_pk_add_f32 v[210:211], v[50:51], v[142:143]
	v_pk_add_f32 v[212:213], v[52:53], v[144:145]
	v_pk_mul_f32 v[206:207], v[206:207], v[176:177]
	v_exp_f32_e32 v206, v206
	v_pk_mul_f32 v[208:209], v[208:209], v[176:177]
	v_exp_f32_e32 v207, v207
	v_pk_mul_f32 v[210:211], v[210:211], v[176:177]
	v_exp_f32_e32 v208, v208
	v_pk_mul_f32 v[212:213], v[212:213], v[176:177]
	v_exp_f32_e32 v209, v209
	v_pk_add_f32 v[214:215], v[62:63], v[130:131]
	v_exp_f32_e32 v210, v210
	v_pk_add_f32 v[216:217], v[64:65], v[132:133]
	v_exp_f32_e32 v211, v211
	v_pk_add_f32 v[218:219], v[54:55], v[134:135]
	v_exp_f32_e32 v212, v212
	v_pk_add_f32 v[220:221], v[56:57], v[136:137]
	v_exp_f32_e32 v213, v213
	v_pk_add_f32 v[206:207], v[206:207], 1.0 op_sel_hi:[1,0]
	v_rcp_f32_e32 v206, v206
	v_pk_add_f32 v[208:209], v[208:209], 1.0 op_sel_hi:[1,0]
	v_rcp_f32_e32 v207, v207
	v_pk_add_f32 v[210:211], v[210:211], 1.0 op_sel_hi:[1,0]
	v_rcp_f32_e32 v208, v208
	v_pk_add_f32 v[212:213], v[212:213], 1.0 op_sel_hi:[1,0]
	v_rcp_f32_e32 v209, v209
	v_pk_mul_f32 v[214:215], v[214:215], v[206:207]
	v_rcp_f32_e32 v210, v210
	v_pk_mul_f32 v[216:217], v[216:217], v[208:209]
	v_rcp_f32_e32 v211, v211
	v_cvt_pk_bf16_f32 v222, v214, v215
	v_rcp_f32_e32 v212, v212
	v_pk_mul_f32 v[218:219], v[218:219], v[210:211]
	v_rcp_f32_e32 v213, v213
	v_cvt_pk_bf16_f32 v223, v216, v217
	v_pk_mul_f32 v[220:221], v[220:221], v[212:213]
	v_cvt_pk_bf16_f32 v224, v218, v219
	v_cvt_pk_bf16_f32 v225, v220, v221
	v_pk_add_f32 v[226:227], v[42:43], v[138:139]
	v_permlane16_swap_b32_e32 v222, v224
	v_permlane16_swap_b32_e32 v223, v225
	global_store_dwordx4 v[172:173], v[222:225], off sc1
	v_pk_add_f32 v[228:229], v[44:45], v[140:141]
	v_lshl_add_u64 v[172:173], v[172:173], 0, s[6:7]
	v_pk_add_f32 v[236:237], v[34:35], v[142:143]
	v_pk_add_f32 v[238:239], v[36:37], v[144:145]
	v_pk_mul_f32 v[226:227], v[226:227], v[176:177]
	v_exp_f32_e32 v226, v226
	v_pk_mul_f32 v[228:229], v[228:229], v[176:177]
	v_exp_f32_e32 v227, v227
	v_pk_mul_f32 v[236:237], v[236:237], v[176:177]
	v_exp_f32_e32 v228, v228
	v_pk_mul_f32 v[238:239], v[238:239], v[176:177]
	v_exp_f32_e32 v229, v229
	v_pk_add_f32 v[240:241], v[46:47], v[130:131]
	v_exp_f32_e32 v236, v236
	v_pk_add_f32 v[242:243], v[48:49], v[132:133]
	v_exp_f32_e32 v237, v237
	v_pk_add_f32 v[244:245], v[38:39], v[134:135]
	v_exp_f32_e32 v238, v238
	v_pk_add_f32 v[246:247], v[40:41], v[136:137]
	v_exp_f32_e32 v239, v239
	v_pk_add_f32 v[226:227], v[226:227], 1.0 op_sel_hi:[1,0]
	v_rcp_f32_e32 v226, v226
	v_pk_add_f32 v[228:229], v[228:229], 1.0 op_sel_hi:[1,0]
	v_rcp_f32_e32 v227, v227
	v_pk_add_f32 v[236:237], v[236:237], 1.0 op_sel_hi:[1,0]
	v_rcp_f32_e32 v228, v228
	v_pk_add_f32 v[238:239], v[238:239], 1.0 op_sel_hi:[1,0]
	v_rcp_f32_e32 v229, v229
	v_pk_mul_f32 v[240:241], v[240:241], v[226:227]
	v_rcp_f32_e32 v236, v236
	v_pk_mul_f32 v[242:243], v[242:243], v[228:229]
	v_rcp_f32_e32 v237, v237
	v_cvt_pk_bf16_f32 v164, v240, v241
	v_rcp_f32_e32 v238, v238
	v_pk_mul_f32 v[244:245], v[244:245], v[236:237]
	v_rcp_f32_e32 v239, v239
	v_cvt_pk_bf16_f32 v165, v242, v243
	v_pk_mul_f32 v[246:247], v[246:247], v[238:239]
	v_cvt_pk_bf16_f32 v166, v244, v245
	v_cvt_pk_bf16_f32 v167, v246, v247
	v_pk_add_f32 v[206:207], v[26:27], v[138:139]
	v_permlane16_swap_b32_e32 v164, v166
	v_permlane16_swap_b32_e32 v165, v167
	global_store_dwordx4 v[172:173], v[164:167], off sc1
	v_pk_add_f32 v[208:209], v[28:29], v[140:141]
	v_lshl_add_u64 v[172:173], v[172:173], 0, s[6:7]
	v_pk_add_f32 v[210:211], v[18:19], v[142:143]
	v_pk_add_f32 v[212:213], v[20:21], v[144:145]
	v_pk_mul_f32 v[206:207], v[206:207], v[176:177]
	v_exp_f32_e32 v206, v206
	v_pk_mul_f32 v[208:209], v[208:209], v[176:177]
	v_exp_f32_e32 v207, v207
	v_pk_mul_f32 v[210:211], v[210:211], v[176:177]
	v_exp_f32_e32 v208, v208
	v_pk_mul_f32 v[212:213], v[212:213], v[176:177]
	v_exp_f32_e32 v209, v209
	v_pk_add_f32 v[214:215], v[30:31], v[130:131]
	v_exp_f32_e32 v210, v210
	v_pk_add_f32 v[216:217], v[32:33], v[132:133]
	v_exp_f32_e32 v211, v211
	v_pk_add_f32 v[218:219], v[22:23], v[134:135]
	v_exp_f32_e32 v212, v212
	v_pk_add_f32 v[220:221], v[24:25], v[136:137]
	v_exp_f32_e32 v213, v213
	v_pk_add_f32 v[206:207], v[206:207], 1.0 op_sel_hi:[1,0]
	v_rcp_f32_e32 v206, v206
	v_pk_add_f32 v[208:209], v[208:209], 1.0 op_sel_hi:[1,0]
	v_rcp_f32_e32 v207, v207
	v_pk_add_f32 v[210:211], v[210:211], 1.0 op_sel_hi:[1,0]
	v_rcp_f32_e32 v208, v208
	v_pk_add_f32 v[212:213], v[212:213], 1.0 op_sel_hi:[1,0]
	v_rcp_f32_e32 v209, v209
	v_pk_mul_f32 v[214:215], v[214:215], v[206:207]
	v_rcp_f32_e32 v210, v210
	v_pk_mul_f32 v[216:217], v[216:217], v[208:209]
	v_rcp_f32_e32 v211, v211
	v_cvt_pk_bf16_f32 v222, v214, v215
	v_rcp_f32_e32 v212, v212
	v_pk_mul_f32 v[218:219], v[218:219], v[210:211]
	v_rcp_f32_e32 v213, v213
	v_cvt_pk_bf16_f32 v223, v216, v217
	v_pk_mul_f32 v[220:221], v[220:221], v[212:213]
	v_cvt_pk_bf16_f32 v224, v218, v219
	v_cvt_pk_bf16_f32 v225, v220, v221
	v_pk_add_f32 v[226:227], v[10:11], v[138:139]
	v_permlane16_swap_b32_e32 v222, v224
	v_permlane16_swap_b32_e32 v223, v225
	global_store_dwordx4 v[172:173], v[222:225], off sc1
	v_pk_add_f32 v[228:229], v[12:13], v[140:141]
	v_lshl_add_u64 v[172:173], v[172:173], 0, s[6:7]
	v_pk_add_f32 v[236:237], v[2:3], v[142:143]
	v_pk_add_f32 v[238:239], v[4:5], v[144:145]
	v_pk_mul_f32 v[226:227], v[226:227], v[176:177]
	v_exp_f32_e32 v226, v226
	v_pk_mul_f32 v[228:229], v[228:229], v[176:177]
	v_exp_f32_e32 v227, v227
	v_pk_mul_f32 v[236:237], v[236:237], v[176:177]
	v_exp_f32_e32 v228, v228
	v_pk_mul_f32 v[238:239], v[238:239], v[176:177]
	v_exp_f32_e32 v229, v229
	v_pk_add_f32 v[240:241], v[14:15], v[130:131]
	v_exp_f32_e32 v236, v236
	v_pk_add_f32 v[242:243], v[16:17], v[132:133]
	v_exp_f32_e32 v237, v237
	v_pk_add_f32 v[244:245], v[6:7], v[134:135]
	v_exp_f32_e32 v238, v238
	v_pk_add_f32 v[246:247], v[8:9], v[136:137]
	v_exp_f32_e32 v239, v239
	v_pk_add_f32 v[226:227], v[226:227], 1.0 op_sel_hi:[1,0]
	v_rcp_f32_e32 v226, v226
	v_pk_add_f32 v[228:229], v[228:229], 1.0 op_sel_hi:[1,0]
	v_rcp_f32_e32 v227, v227
	v_pk_add_f32 v[236:237], v[236:237], 1.0 op_sel_hi:[1,0]
	v_rcp_f32_e32 v228, v228
	v_pk_add_f32 v[238:239], v[238:239], 1.0 op_sel_hi:[1,0]
	v_rcp_f32_e32 v229, v229
	v_pk_mul_f32 v[240:241], v[240:241], v[226:227]
	v_rcp_f32_e32 v236, v236
	v_pk_mul_f32 v[242:243], v[242:243], v[228:229]
	v_rcp_f32_e32 v237, v237
	v_cvt_pk_bf16_f32 v164, v240, v241
	v_rcp_f32_e32 v238, v238
	v_pk_mul_f32 v[244:245], v[244:245], v[236:237]
	v_rcp_f32_e32 v239, v239
	v_cvt_pk_bf16_f32 v165, v242, v243
	v_pk_mul_f32 v[246:247], v[246:247], v[238:239]
	v_cvt_pk_bf16_f32 v166, v244, v245
	v_cvt_pk_bf16_f32 v167, v246, v247
	s_nop 0
	v_permlane16_swap_b32_e32 v164, v166
	v_permlane16_swap_b32_e32 v165, v167
	global_store_dwordx4 v[172:173], v[164:167], off sc1
	s_branch .LBB0_816

.Lrettv_fast:
	s_and_b64 vcc, exec, s[0:1]
	s_cbranch_vccnz .Lrettv_fast_wt
	v_readlane_b32 s4, v253, 36
	v_mov_b32_e32 v170, s4
	ds_read_b64 v[174:175], v170
	v_ashrrev_i32_e32 v161, 31, v160
	v_lshlrev_b64 v[172:173], 8, v[160:161]
	v_ashrrev_i32_e32 v168, 7, v162
	v_ashrrev_i32_e32 v169, 31, v168
	v_lshlrev_b64 v[168:169], 19, v[168:169]
	v_and_b32_e32 v170, 0x7c, v146
	v_lshlrev_b32_e32 v171, 2, v203
	v_sub_u32_e32 v170, v170, v171
	v_and_b32_e32 v171, 1, v203
	v_lshl_add_u32 v170, v171, 4, v170
	v_lshrrev_b32_e32 v171, 1, v203
	v_lshl_add_u32 v170, v171, 3, v170
	v_lshlrev_b32_e32 v170, 1, v170
	v_mov_b32_e32 v171, 0
	s_mov_b32 s4, 0xfffc0000
	s_mov_b32 s5, -1
	s_waitcnt lgkmcnt(0)
	v_lshl_add_u64 v[172:173], v[172:173], 0, v[174:175]
	v_lshl_add_u64 v[172:173], v[172:173], 0, s[4:5]
	v_lshl_add_u64 v[172:173], v[172:173], 0, v[168:169]
	v_lshl_add_u64 v[172:173], v[172:173], 0, v[170:171]
	s_mov_b64 s[4:5], 0x80000
	v_lshl_add_u64 v[174:175], v[172:173], 0, s[4:5]
	s_mov_b64 s[6:7], 0x1000
	s_mov_b64 s[8:9], 0x5000
	v_cvt_pk_bf16_f32 v206, v126, v127
	v_cvt_pk_bf16_f32 v207, v128, v129
	v_cvt_pk_bf16_f32 v208, v118, v119
	v_cvt_pk_bf16_f32 v209, v120, v121
	v_cvt_pk_bf16_f32 v210, v122, v123
	v_cvt_pk_bf16_f32 v211, v124, v125
	v_cvt_pk_bf16_f32 v212, v114, v115
	v_cvt_pk_bf16_f32 v213, v116, v117
	v_permlane16_swap_b32_e32 v206, v208
	v_permlane16_swap_b32_e32 v207, v209
	global_store_dwordx4 v[172:173], v[206:209], off
	s_nop 1
	v_permlane16_swap_b32_e32 v210, v212
	v_permlane16_swap_b32_e32 v211, v213
	global_store_dwordx4 v[174:175], v[210:213], off
	s_nop 0
	v_lshl_add_u64 v[172:173], v[172:173], 0, s[6:7]
	v_lshl_add_u64 v[174:175], v[174:175], 0, s[6:7]
	v_cvt_pk_bf16_f32 v214, v110, v111
	v_cvt_pk_bf16_f32 v215, v112, v113
	v_cvt_pk_bf16_f32 v216, v102, v103
	v_cvt_pk_bf16_f32 v217, v104, v105
	v_cvt_pk_bf16_f32 v218, v106, v107
	v_cvt_pk_bf16_f32 v219, v108, v109
	v_cvt_pk_bf16_f32 v220, v98, v99
	v_cvt_pk_bf16_f32 v221, v100, v101
	v_permlane16_swap_b32_e32 v214, v216
	v_permlane16_swap_b32_e32 v215, v217
	global_store_dwordx4 v[172:173], v[214:217], off
	s_nop 1
	v_permlane16_swap_b32_e32 v218, v220
	v_permlane16_swap_b32_e32 v219, v221
	global_store_dwordx4 v[174:175], v[218:221], off
	s_nop 0
	v_lshl_add_u64 v[172:173], v[172:173], 0, s[6:7]
	v_lshl_add_u64 v[174:175], v[174:175], 0, s[6:7]
	v_cvt_pk_bf16_f32 v222, v94, v95
	v_cvt_pk_bf16_f32 v223, v96, v97
	v_cvt_pk_bf16_f32 v224, v86, v87
	v_cvt_pk_bf16_f32 v225, v88, v89
	v_cvt_pk_bf16_f32 v226, v90, v91
	v_cvt_pk_bf16_f32 v227, v92, v93
	v_cvt_pk_bf16_f32 v228, v82, v83
	v_cvt_pk_bf16_f32 v229, v84, v85
	v_permlane16_swap_b32_e32 v222, v224
	v_permlane16_swap_b32_e32 v223, v225
	global_store_dwordx4 v[172:173], v[222:225], off
	s_nop 1
	v_permlane16_swap_b32_e32 v226, v228
	v_permlane16_swap_b32_e32 v227, v229
	global_store_dwordx4 v[174:175], v[226:229], off
	s_nop 0
	v_lshl_add_u64 v[172:173], v[172:173], 0, s[6:7]
	v_lshl_add_u64 v[174:175], v[174:175], 0, s[6:7]
	v_cvt_pk_bf16_f32 v236, v78, v79
	v_cvt_pk_bf16_f32 v237, v80, v81
	v_cvt_pk_bf16_f32 v238, v70, v71
	v_cvt_pk_bf16_f32 v239, v72, v73
	v_cvt_pk_bf16_f32 v240, v74, v75
	v_cvt_pk_bf16_f32 v241, v76, v77
	v_cvt_pk_bf16_f32 v242, v66, v67
	v_cvt_pk_bf16_f32 v243, v68, v69
	v_permlane16_swap_b32_e32 v236, v238
	v_permlane16_swap_b32_e32 v237, v239
	global_store_dwordx4 v[172:173], v[236:239], off
	s_nop 1
	v_permlane16_swap_b32_e32 v240, v242
	v_permlane16_swap_b32_e32 v241, v243
	global_store_dwordx4 v[174:175], v[240:243], off
	s_nop 0
	v_lshl_add_u64 v[172:173], v[172:173], 0, s[8:9]
	v_lshl_add_u64 v[174:175], v[174:175], 0, s[8:9]
	v_cvt_pk_bf16_f32 v244, v62, v63
	v_cvt_pk_bf16_f32 v245, v64, v65
	v_cvt_pk_bf16_f32 v246, v54, v55
	v_cvt_pk_bf16_f32 v247, v56, v57
	v_cvt_pk_bf16_f32 v206, v58, v59
	v_cvt_pk_bf16_f32 v207, v60, v61
	v_cvt_pk_bf16_f32 v208, v50, v51
	v_cvt_pk_bf16_f32 v209, v52, v53
	v_permlane16_swap_b32_e32 v244, v246
	v_permlane16_swap_b32_e32 v245, v247
	global_store_dwordx4 v[172:173], v[244:247], off
	s_nop 1
	v_permlane16_swap_b32_e32 v206, v208
	v_permlane16_swap_b32_e32 v207, v209
	global_store_dwordx4 v[174:175], v[206:209], off
	s_nop 0
	v_lshl_add_u64 v[172:173], v[172:173], 0, s[6:7]
	v_lshl_add_u64 v[174:175], v[174:175], 0, s[6:7]
	v_cvt_pk_bf16_f32 v210, v46, v47
	v_cvt_pk_bf16_f32 v211, v48, v49
	v_cvt_pk_bf16_f32 v212, v38, v39
	v_cvt_pk_bf16_f32 v213, v40, v41
	v_cvt_pk_bf16_f32 v214, v42, v43
	v_cvt_pk_bf16_f32 v215, v44, v45
	v_cvt_pk_bf16_f32 v216, v34, v35
	v_cvt_pk_bf16_f32 v217, v36, v37
	v_permlane16_swap_b32_e32 v210, v212
	v_permlane16_swap_b32_e32 v211, v213
	global_store_dwordx4 v[172:173], v[210:213], off
	s_nop 1
	v_permlane16_swap_b32_e32 v214, v216
	v_permlane16_swap_b32_e32 v215, v217
	global_store_dwordx4 v[174:175], v[214:217], off
	s_nop 0
	v_lshl_add_u64 v[172:173], v[172:173], 0, s[6:7]
	v_lshl_add_u64 v[174:175], v[174:175], 0, s[6:7]
	v_cvt_pk_bf16_f32 v218, v30, v31
	v_cvt_pk_bf16_f32 v219, v32, v33
	v_cvt_pk_bf16_f32 v220, v22, v23
	v_cvt_pk_bf16_f32 v221, v24, v25
	v_cvt_pk_bf16_f32 v222, v26, v27
	v_cvt_pk_bf16_f32 v223, v28, v29
	v_cvt_pk_bf16_f32 v224, v18, v19
	v_cvt_pk_bf16_f32 v225, v20, v21
	v_permlane16_swap_b32_e32 v218, v220
	v_permlane16_swap_b32_e32 v219, v221
	global_store_dwordx4 v[172:173], v[218:221], off
	s_nop 1
	v_permlane16_swap_b32_e32 v222, v224
	v_permlane16_swap_b32_e32 v223, v225
	global_store_dwordx4 v[174:175], v[222:225], off
	s_nop 0
	v_lshl_add_u64 v[172:173], v[172:173], 0, s[6:7]
	v_lshl_add_u64 v[174:175], v[174:175], 0, s[6:7]
	v_cvt_pk_bf16_f32 v226, v14, v15
	v_cvt_pk_bf16_f32 v227, v16, v17
	v_cvt_pk_bf16_f32 v228, v6, v7
	v_cvt_pk_bf16_f32 v229, v8, v9
	v_cvt_pk_bf16_f32 v236, v10, v11
	v_cvt_pk_bf16_f32 v237, v12, v13
	v_cvt_pk_bf16_f32 v238, v2, v3
	v_cvt_pk_bf16_f32 v239, v4, v5
	v_permlane16_swap_b32_e32 v226, v228
	v_permlane16_swap_b32_e32 v227, v229
	global_store_dwordx4 v[172:173], v[226:229], off
	s_nop 1
	v_permlane16_swap_b32_e32 v236, v238
	v_permlane16_swap_b32_e32 v237, v239
	global_store_dwordx4 v[174:175], v[236:239], off
	s_branch .LBB0_816
.Lrettv_fast_wt:
	v_readlane_b32 s4, v253, 36
	v_mov_b32_e32 v170, s4
	ds_read_b64 v[174:175], v170
	v_ashrrev_i32_e32 v161, 31, v160
	v_lshlrev_b64 v[172:173], 8, v[160:161]
	v_ashrrev_i32_e32 v168, 7, v162
	v_ashrrev_i32_e32 v169, 31, v168
	v_lshlrev_b64 v[168:169], 19, v[168:169]
	v_and_b32_e32 v170, 0x7c, v146
	v_lshlrev_b32_e32 v171, 2, v203
	v_sub_u32_e32 v170, v170, v171
	v_and_b32_e32 v171, 1, v203
	v_lshl_add_u32 v170, v171, 4, v170
	v_lshrrev_b32_e32 v171, 1, v203
	v_lshl_add_u32 v170, v171, 3, v170
	v_lshlrev_b32_e32 v170, 1, v170
	v_mov_b32_e32 v171, 0
	s_mov_b32 s4, 0xfffc0000
	s_mov_b32 s5, -1
	s_waitcnt lgkmcnt(0)
	v_lshl_add_u64 v[172:173], v[172:173], 0, v[174:175]
	v_lshl_add_u64 v[172:173], v[172:173], 0, s[4:5]
	v_lshl_add_u64 v[172:173], v[172:173], 0, v[168:169]
	v_lshl_add_u64 v[172:173], v[172:173], 0, v[170:171]
	s_mov_b64 s[4:5], 0x80000
	v_lshl_add_u64 v[174:175], v[172:173], 0, s[4:5]
	s_mov_b64 s[6:7], 0x1000
	s_mov_b64 s[8:9], 0x5000
	v_cvt_pk_bf16_f32 v206, v126, v127
	v_cvt_pk_bf16_f32 v207, v128, v129
	v_cvt_pk_bf16_f32 v208, v118, v119
	v_cvt_pk_bf16_f32 v209, v120, v121
	v_cvt_pk_bf16_f32 v210, v122, v123
	v_cvt_pk_bf16_f32 v211, v124, v125
	v_cvt_pk_bf16_f32 v212, v114, v115
	v_cvt_pk_bf16_f32 v213, v116, v117
	v_permlane16_swap_b32_e32 v206, v208
	v_permlane16_swap_b32_e32 v207, v209
	global_store_dwordx4 v[172:173], v[206:209], off sc1
	s_nop 1
	v_permlane16_swap_b32_e32 v210, v212
	v_permlane16_swap_b32_e32 v211, v213
	global_store_dwordx4 v[174:175], v[210:213], off sc1
	s_nop 0
	v_lshl_add_u64 v[172:173], v[172:173], 0, s[6:7]
	v_lshl_add_u64 v[174:175], v[174:175], 0, s[6:7]
	v_cvt_pk_bf16_f32 v214, v110, v111
	v_cvt_pk_bf16_f32 v215, v112, v113
	v_cvt_pk_bf16_f32 v216, v102, v103
	v_cvt_pk_bf16_f32 v217, v104, v105
	v_cvt_pk_bf16_f32 v218, v106, v107
	v_cvt_pk_bf16_f32 v219, v108, v109
	v_cvt_pk_bf16_f32 v220, v98, v99
	v_cvt_pk_bf16_f32 v221, v100, v101
	v_permlane16_swap_b32_e32 v214, v216
	v_permlane16_swap_b32_e32 v215, v217
	global_store_dwordx4 v[172:173], v[214:217], off sc1
	s_nop 1
	v_permlane16_swap_b32_e32 v218, v220
	v_permlane16_swap_b32_e32 v219, v221
	global_store_dwordx4 v[174:175], v[218:221], off sc1
	s_nop 0
	v_lshl_add_u64 v[172:173], v[172:173], 0, s[6:7]
	v_lshl_add_u64 v[174:175], v[174:175], 0, s[6:7]
	v_cvt_pk_bf16_f32 v222, v94, v95
	v_cvt_pk_bf16_f32 v223, v96, v97
	v_cvt_pk_bf16_f32 v224, v86, v87
	v_cvt_pk_bf16_f32 v225, v88, v89
	v_cvt_pk_bf16_f32 v226, v90, v91
	v_cvt_pk_bf16_f32 v227, v92, v93
	v_cvt_pk_bf16_f32 v228, v82, v83
	v_cvt_pk_bf16_f32 v229, v84, v85
	v_permlane16_swap_b32_e32 v222, v224
	v_permlane16_swap_b32_e32 v223, v225
	global_store_dwordx4 v[172:173], v[222:225], off sc1
	s_nop 1
	v_permlane16_swap_b32_e32 v226, v228
	v_permlane16_swap_b32_e32 v227, v229
	global_store_dwordx4 v[174:175], v[226:229], off sc1
	s_nop 0
	v_lshl_add_u64 v[172:173], v[172:173], 0, s[6:7]
	v_lshl_add_u64 v[174:175], v[174:175], 0, s[6:7]
	v_cvt_pk_bf16_f32 v236, v78, v79
	v_cvt_pk_bf16_f32 v237, v80, v81
	v_cvt_pk_bf16_f32 v238, v70, v71
	v_cvt_pk_bf16_f32 v239, v72, v73
	v_cvt_pk_bf16_f32 v240, v74, v75
	v_cvt_pk_bf16_f32 v241, v76, v77
	v_cvt_pk_bf16_f32 v242, v66, v67
	v_cvt_pk_bf16_f32 v243, v68, v69
	v_permlane16_swap_b32_e32 v236, v238
	v_permlane16_swap_b32_e32 v237, v239
	global_store_dwordx4 v[172:173], v[236:239], off sc1
	s_nop 1
	v_permlane16_swap_b32_e32 v240, v242
	v_permlane16_swap_b32_e32 v241, v243
	global_store_dwordx4 v[174:175], v[240:243], off sc1
	s_nop 0
	v_lshl_add_u64 v[172:173], v[172:173], 0, s[8:9]
	v_lshl_add_u64 v[174:175], v[174:175], 0, s[8:9]
	v_cvt_pk_bf16_f32 v244, v62, v63
	v_cvt_pk_bf16_f32 v245, v64, v65
	v_cvt_pk_bf16_f32 v246, v54, v55
	v_cvt_pk_bf16_f32 v247, v56, v57
	v_cvt_pk_bf16_f32 v206, v58, v59
	v_cvt_pk_bf16_f32 v207, v60, v61
	v_cvt_pk_bf16_f32 v208, v50, v51
	v_cvt_pk_bf16_f32 v209, v52, v53
	v_permlane16_swap_b32_e32 v244, v246
	v_permlane16_swap_b32_e32 v245, v247
	global_store_dwordx4 v[172:173], v[244:247], off sc1
	s_nop 1
	v_permlane16_swap_b32_e32 v206, v208
	v_permlane16_swap_b32_e32 v207, v209
	global_store_dwordx4 v[174:175], v[206:209], off sc1
	s_nop 0
	v_lshl_add_u64 v[172:173], v[172:173], 0, s[6:7]
	v_lshl_add_u64 v[174:175], v[174:175], 0, s[6:7]
	v_cvt_pk_bf16_f32 v210, v46, v47
	v_cvt_pk_bf16_f32 v211, v48, v49
	v_cvt_pk_bf16_f32 v212, v38, v39
	v_cvt_pk_bf16_f32 v213, v40, v41
	v_cvt_pk_bf16_f32 v214, v42, v43
	v_cvt_pk_bf16_f32 v215, v44, v45
	v_cvt_pk_bf16_f32 v216, v34, v35
	v_cvt_pk_bf16_f32 v217, v36, v37
	v_permlane16_swap_b32_e32 v210, v212
	v_permlane16_swap_b32_e32 v211, v213
	global_store_dwordx4 v[172:173], v[210:213], off sc1
	s_nop 1
	v_permlane16_swap_b32_e32 v214, v216
	v_permlane16_swap_b32_e32 v215, v217
	global_store_dwordx4 v[174:175], v[214:217], off sc1
	s_nop 0
	v_lshl_add_u64 v[172:173], v[172:173], 0, s[6:7]
	v_lshl_add_u64 v[174:175], v[174:175], 0, s[6:7]
	v_cvt_pk_bf16_f32 v218, v30, v31
	v_cvt_pk_bf16_f32 v219, v32, v33
	v_cvt_pk_bf16_f32 v220, v22, v23
	v_cvt_pk_bf16_f32 v221, v24, v25
	v_cvt_pk_bf16_f32 v222, v26, v27
	v_cvt_pk_bf16_f32 v223, v28, v29
	v_cvt_pk_bf16_f32 v224, v18, v19
	v_cvt_pk_bf16_f32 v225, v20, v21
	v_permlane16_swap_b32_e32 v218, v220
	v_permlane16_swap_b32_e32 v219, v221
	global_store_dwordx4 v[172:173], v[218:221], off sc1
	s_nop 1
	v_permlane16_swap_b32_e32 v222, v224
	v_permlane16_swap_b32_e32 v223, v225
	global_store_dwordx4 v[174:175], v[222:225], off sc1
	s_nop 0
	v_lshl_add_u64 v[172:173], v[172:173], 0, s[6:7]
	v_lshl_add_u64 v[174:175], v[174:175], 0, s[6:7]
	v_cvt_pk_bf16_f32 v226, v14, v15
	v_cvt_pk_bf16_f32 v227, v16, v17
	v_cvt_pk_bf16_f32 v228, v6, v7
	v_cvt_pk_bf16_f32 v229, v8, v9
	v_cvt_pk_bf16_f32 v236, v10, v11
	v_cvt_pk_bf16_f32 v237, v12, v13
	v_cvt_pk_bf16_f32 v238, v2, v3
	v_cvt_pk_bf16_f32 v239, v4, v5
	v_permlane16_swap_b32_e32 v226, v228
	v_permlane16_swap_b32_e32 v227, v229
	global_store_dwordx4 v[172:173], v[226:229], off sc1
	s_nop 1
	v_permlane16_swap_b32_e32 v236, v238
	v_permlane16_swap_b32_e32 v237, v239
	global_store_dwordx4 v[174:175], v[236:239], off sc1
	s_branch .LBB0_816
